# only change: conv f32 k/v stores as whole 128-byte lines (two 8-byte loads per lane), no nt
# baseline (speedup 1.0000x reference)
; #define LAS __attribute__((address_space(3)))
; #define ATT_WAIT_BAR() asm volatile("s_waitcnt vmcnt(0) lgkmcnt(0)\n\ts_barrier" ::: "memory")
; __device__ __forceinline__ int next_unit(unsigned* ctr, LAS unsigned char* lds) {
;     ATT_WAIT_BAR();
;     if (threadIdx.x == 0) *(LAS unsigned*)(lds + A_UNIT) = __hip_atomic_fetch_add(ctr, 1u, __ATOMIC_RELAXED, __HIP_MEMORY_SCOPE_AGENT);
;     ATT_WAIT_BAR();
;     return (int)*(volatile LAS unsigned*)(lds + A_UNIT);
; }
.LBB0_254:
	s_or_b64 exec, exec, s[0:1]
	s_add_i32 s0, s3, 0
	s_add_i32 s0, s0, 0x21c10
	s_waitcnt vmcnt(0) lgkmcnt(0)
	s_barrier
	v_mov_b32_e32 v1, s0
	ds_read_b32 v1, v1
	s_movk_i32 s0, 0x1100
	s_xor_b32 s2, s2, 1
	s_waitcnt lgkmcnt(0)
	v_cmp_gt_i32_e32 vcc, s0, v1
	s_cbranch_vccz .LBB0_502
.LBB0_255:
	v_mov_b32_e32 v189, v5
	s_and_saveexec_b64 s[0:1], s[72:73]
	s_cbranch_execz .LBB0_259
	s_mov_b64 s[6:7], exec
	v_mbcnt_lo_u32_b32 v2, s6, 0
	v_mbcnt_hi_u32_b32 v2, s7, v2
	v_cmp_eq_u32_e32 vcc, 0, v2
	s_and_saveexec_b64 s[4:5], vcc
	s_cbranch_execz .LBB0_258
	s_bcnt1_i32_b64 s3, s[6:7]
	v_readlane_b32 s6, v242, 16
	v_mov_b32_e32 v3, s3
	v_readlane_b32 s7, v242, 17
	s_nop 4
	global_atomic_add v3, v5, v3, s[6:7] sc0
.LBB0_258:
	s_or_b64 exec, exec, s[4:5]
	s_waitcnt vmcnt(0)
	v_readfirstlane_b32 s3, v3
	s_nop 1
	v_add_u32_e32 v189, s3, v2

; #define LAS __attribute__((address_space(3)))
; #define ATT_DMA(jt, slot) do { glds16(ksrc + (size_t)(jt) * 64 * D, (unsigned)__builtin_amdgcn_readfirstlane(lds0 + A_K + (slot) * 8192 + wid * 1024)); \
;                                glds16(vsrc + (size_t)(jt) * 64 * D, (unsigned)__builtin_amdgcn_readfirstlane(lds0 + A_V + (slot) * 8192 + wid * 1024)); } while (0)
; __device__ __forceinline__ void prompt_unit_sb(const Args& a, int l, int b, int h, int qb, LAS unsigned char* lds) {
;     int tid_ = threadIdx.x; asm volatile("" : "+v"(tid_));
;     const int tid = tid_, lane = tid & 63, r32 = lane & 31, hi = lane >> 5, wid = __builtin_amdgcn_readfirstlane(tid >> 6);
;     f16x8 T00, T01; make_tri(T00, T01, r32, hi);
;     const int q0 = qb * 256, jb = q0 / 64, jd = jb + (wid >> 1);
;     const int col = W + h * HD;
;     const size_t rowb = (size_t)b * T;
;     const bf16* Kh = (const bf16*)(a.ws + WS_K) + rowb * D + col; const bf16* Vh = (const bf16*)(a.ws + WS_V) + rowb * D + col;
;     const unsigned lds0 = (unsigned)(uintptr_t)lds;
;     const bf16* ksrc = Kh + (size_t)lane * D + wid * 8;
;     const bf16* vsrc = Vh + (size_t)(16 * (wid & 3) + (lane >> 2)) * D + (wid >> 2) * 32 + (lane & 3) * 8;
;     ...
;     ATT_DMA(jb + 3); ATT_DMA(jb + 2); ATT_DMA(jb + 1); ATT_DMA(jb);
;     if (jb >= 4) { ATT_DMA(jb - 1); ATT_DMA(jb - 2); ATT_DMA(jb - 3); }
;     bf16x8 qr[4];
;     { const bf16* Qw = (const bf16*)(a.ws + WS_Q) + (rowb + q0 + wid * 32 + r32) * D + col;
; #pragma unroll
;       for (int d0 = 0; d0 < 4; ++d0) qr[d0] = *(const bf16x8*)(Qw + d0 * 16 + hi * 8); }
;     const lds_cptr vp0 = (lds_cptr)lds + B_V + ((lane >> 4) & 1) * 32 + (lane & 3) * 8 + (4 * hi + ((lane & 15) >> 2)) * 64;
;     const int qlim = 32 * (wid & 1) + r32;
;     LAS float* wsf = (LAS float*)(lds + B_WSF) + wid * 64;
;     LAS unsigned* flags = (LAS unsigned*)(lds + B_FLAG);
;     FoxState st; st.m = 0.f; st.l = 0.f; st.mq = (bf16x8){}; st.o[0] = (f32x16){}; st.o[1] = (f32x16){};
;     float R = 0.f; bool done = false;
;     { ConvRegs cv; conv_load(cv, a, rowb + q0 + wid * 32, col, lane); conv_store<1>(cv, a, l, h, rowb + q0 + wid * 32, lane); }
.LBB0_267:
	s_lshl_b32 s0, s4, 8
	s_ashr_i32 s4, s6, 7
	s_ashr_i32 s1, s0, 31
	v_lshrrev_b32_e32 v54, 5, v2
	s_add_u32 s0, s0, s7
	v_and_b32_e32 v169, 31, v19
	v_lshlrev_b32_e32 v55, 2, v54
	s_addc_u32 s1, s1, 0
	s_lshl_b32 s6, s82, 5
	v_cmp_lt_u32_e32 vcc, v55, v169
	v_or_b32_e32 v56, 16, v55
	s_ashr_i32 s7, s6, 31
	v_cndmask_b32_e64 v14, v181, 0, vcc
	v_cmp_lt_u32_e32 vcc, v56, v169
	v_or_b32_e32 v58, 1, v55
	s_add_u32 s78, s0, s6
	v_cndmask_b32_e64 v26, v181, 0, vcc
	v_or_b32_e32 v57, 2, v55
	v_cmp_lt_u32_e32 vcc, v58, v169
	s_addc_u32 s79, s1, s7
	v_or_b32_e32 v60, 17, v55
	v_cndmask_b32_e64 v15, v181, 0, vcc
	v_cmp_lt_u32_e32 vcc, v57, v169
	v_or_b32_e32 v160, s78, v169
	v_mov_b32_e32 v161, s79
	v_readlane_b32 s0, v242, 22
	v_cndmask_b32_e64 v16, v181, 0, vcc
	v_or_b32_e32 v59, 18, v55
	v_cmp_lt_u32_e32 vcc, v60, v169
	v_lshlrev_b64 v[6:7], 11, v[160:161]
	v_readlane_b32 s1, v242, 23
	v_cndmask_b32_e64 v27, v181, 0, vcc
	v_cmp_lt_u32_e32 vcc, v59, v169
	v_or_b32_e32 v62, 3, v55
	v_lshl_add_u64 v[6:7], s[0:1], 0, v[6:7]
	s_lshl_b32 s0, s5, 1
	s_mov_b32 s1, s87
	v_lshrrev_b32_e32 v1, 3, v2
	v_cndmask_b32_e64 v20, v181, 0, vcc
	v_or_b32_e32 v61, 8, v55
	v_cmp_lt_u32_e32 vcc, v62, v169
	v_lshl_add_u64 v[6:7], v[6:7], 0, s[0:1]
	v_lshlrev_b32_e32 v4, 4, v54
	v_or_b32_e32 v160, s78, v1
	v_cndmask_b32_e64 v17, v181, 0, vcc
	v_cmp_lt_u32_e32 vcc, v61, v169
	v_or_b32_e32 v64, 19, v55
	v_lshl_add_u64 v[24:25], v[6:7], 0, v[4:5]
	v_lshlrev_b32_e32 v4, 3, v2
	v_lshlrev_b64 v[166:167], 11, v[160:161]
	v_readlane_b32 s8, v242, 20
	v_cndmask_b32_e64 v21, v181, 0, vcc
	v_or_b32_e32 v63, 24, v55
	v_cmp_lt_u32_e32 vcc, v64, v169
	v_and_b32_e32 v168, 56, v4
	v_lshl_add_u64 v[6:7], s[94:95], 0, v[166:167]
	v_readlane_b32 s9, v242, 21
	v_cndmask_b32_e64 v22, v181, 0, vcc
	v_cmp_lt_u32_e32 vcc, v63, v169
	v_or_b32_e32 v65, 10, v55
	v_lshl_add_u64 v[6:7], v[6:7], 0, s[0:1]
	v_mov_b32_e32 v4, v168
	v_lshl_add_u64 v[10:11], s[8:9], 0, v[166:167]
	v_cndmask_b32_e64 v23, v181, 0, vcc
	v_or_b32_e32 v66, 9, v55
	v_lshl_add_u64 v[6:7], v[6:7], 0, v[4:5]
	v_cmp_lt_u32_e32 vcc, v65, v169
	v_lshl_add_u64 v[10:11], v[10:11], 0, s[0:1]
	global_load_dwordx2 v[8:9], v[6:7], off offset:1088
	global_load_dwordx2 v[6:7], v[6:7], off offset:1024
	v_cndmask_b32_e64 v28, v181, 0, vcc
	v_cmp_lt_u32_e32 vcc, v66, v169
	v_or_b32_e32 v67, 26, v55
	v_lshl_add_u64 v[10:11], v[10:11], 0, v[4:5]
	v_cndmask_b32_e64 v29, v181, 0, vcc
	v_or_b32_e32 v68, 25, v55
	global_load_dwordx2 v[12:13], v[10:11], off offset:1088
	global_load_dwordx2 v[10:11], v[10:11], off offset:1024
	v_cmp_lt_u32_e32 vcc, v67, v169
	v_or_b32_e32 v69, 11, v55
	v_or_b32_e32 v44, 0x4000, v166
	v_cndmask_b32_e64 v30, v181, 0, vcc
	v_cmp_lt_u32_e32 vcc, v68, v169
	v_mov_b32_e32 v45, v167
	v_or_b32_e32 v70, 27, v55
	v_cndmask_b32_e64 v31, v181, 0, vcc
	v_cmp_lt_u32_e32 vcc, v69, v169
	v_pack_b32_f16 v116, v14, v15
	v_lshl_add_u64 v[14:15], s[94:95], 0, v[44:45]
	v_cndmask_b32_e64 v32, v181, 0, vcc
	v_cmp_lt_u32_e32 vcc, v70, v169
	v_pack_b32_f16 v118, v21, v29
	v_lshl_add_u64 v[14:15], v[14:15], 0, s[0:1]
	v_cndmask_b32_e64 v21, v181, 0, vcc
	v_lshl_add_u64 v[14:15], v[14:15], 0, v[4:5]
	v_pack_b32_f16 v121, v20, v22
	v_pack_b32_f16 v123, v30, v21
	v_lshl_add_u64 v[20:21], s[8:9], 0, v[44:45]
	v_pack_b32_f16 v117, v16, v17
	global_load_dwordx2 v[16:17], v[14:15], off offset:1088
	global_load_dwordx2 v[14:15], v[14:15], off offset:1024
	v_lshl_add_u64 v[20:21], v[20:21], 0, s[0:1]
	v_lshl_add_u64 v[20:21], v[20:21], 0, v[4:5]
	v_pack_b32_f16 v122, v23, v31
	global_load_dwordx2 v[22:23], v[20:21], off offset:1088
	global_load_dwordx2 v[20:21], v[20:21], off offset:1024
	s_nop 0
	global_load_dwordx4 v[124:127], v[24:25], off offset:1024
	global_load_dwordx4 v[128:131], v[24:25], off offset:1056
	global_load_dwordx4 v[132:135], v[24:25], off offset:1088
	global_load_dwordx4 v[136:139], v[24:25], off offset:1120
	v_lshlrev_b32_e32 v24, 1, v19
	v_and_b32_e32 v24, 32, v24
	s_add_i32 s7, 0, 0x10000
	v_or_b32_e32 v46, 0x8000, v166
	v_mov_b32_e32 v47, v167
	v_add3_u32 v3, s7, v24, v3
	v_lshl_add_u64 v[24:25], s[94:95], 0, v[46:47]
	v_lshlrev_b32_e32 v29, 4, v19
	v_pack_b32_f16 v119, v28, v32
	v_lshlrev_b32_e32 v28, 8, v54
	v_lshl_add_u64 v[24:25], v[24:25], 0, s[0:1]
	v_and_b32_e32 v29, 0xc0, v29
	v_lshl_add_u64 v[24:25], v[24:25], 0, v[4:5]
	v_add3_u32 v170, v3, v28, v29
	v_lshl_add_u64 v[28:29], s[8:9], 0, v[46:47]
	v_pack_b32_f16 v120, v26, v27
	global_load_dwordx2 v[26:27], v[24:25], off offset:1088
	global_load_dwordx2 v[24:25], v[24:25], off offset:1024
	v_lshl_add_u64 v[28:29], v[28:29], 0, s[0:1]
	v_lshl_add_u64 v[28:29], v[28:29], 0, v[4:5]
	global_load_dwordx2 v[30:31], v[28:29], off offset:1088
	global_load_dwordx2 v[28:29], v[28:29], off offset:1024
	v_or_b32_e32 v48, 0xc000, v166
	v_mov_b32_e32 v49, v167
	v_lshl_add_u64 v[32:33], s[94:95], 0, v[48:49]
	v_lshl_add_u64 v[34:35], s[8:9], 0, v[48:49]
	v_lshl_add_u64 v[32:33], v[32:33], 0, s[0:1]
	v_lshl_add_u64 v[34:35], v[34:35], 0, s[0:1]
	v_lshl_add_u64 v[32:33], v[32:33], 0, v[4:5]
	v_lshl_add_u64 v[36:37], v[34:35], 0, v[4:5]
	global_load_dwordx2 v[34:35], v[32:33], off offset:1088
	global_load_dwordx2 v[32:33], v[32:33], off offset:1024
	s_nop 0
	global_load_dwordx2 v[38:39], v[36:37], off offset:1088
	global_load_dwordx2 v[36:37], v[36:37], off offset:1024
	v_and_or_b32 v3, s6, 32, v169
	v_readlane_b32 s6, v242, 24
	v_readlane_b32 s7, v242, 25
	s_lshl_b32 s92, s5, 2
	s_mov_b32 s93, s87
	v_lshl_add_u64 v[40:41], s[6:7], 0, v[166:167]
	v_readlane_b32 s8, v242, 26
	v_lshl_add_u64 v[40:41], v[40:41], 0, s[92:93]
	v_lshlrev_b32_e32 v4, 1, v168
	v_readlane_b32 s9, v242, 27
	v_lshl_add_u64 v[50:51], v[40:41], 0, v[4:5]
	v_lshlrev_b32_e32 v171, 10, v54
	v_lshl_add_u64 v[40:41], s[8:9], 0, v[166:167]
	v_lshl_add_u64 v[40:41], v[40:41], 0, s[92:93]
	v_lshl_add_u64 v[52:53], v[40:41], 0, v[4:5]
	s_lshl_b32 s1, s82, 2
	s_waitcnt vmcnt(0)
; #define LAS __attribute__((address_space(3)))
; __device__ __forceinline__ float bflo(unsigned w) { return __uint_as_float(w << 16); }
; __device__ __forceinline__ float bfhi(unsigned w) { return __uint_as_float(w & 0xffff0000u); }
; template <int TYPE>
; __device__ __forceinline__ void conv_store(const ConvRegs& c, const Args& a, int l, int h, size_t rowq, int lane) {
; #pragma unroll
;     for (int i = 0; i < 4; ++i) { const size_t grow = rowq + i * 8 + (lane >> 3);
;         float* ko = a.out + (TYPE == 0 ? O_FKP : O_SKP) + ((size_t)l * MP + grow) * W + h * HD + (lane & 7) * 8;
;         float* vo = a.out + (TYPE == 0 ? O_FVP : O_SVP) + ((size_t)l * MP + grow) * W + h * HD + (lane & 7) * 8;
;         const u32x4 kw = c.k[i], vw = c.v[i];
;         __builtin_nontemporal_store((f32x4){bflo(kw.x), bfhi(kw.x), bflo(kw.y), bfhi(kw.y)}, (f32x4*)ko); __builtin_nontemporal_store((f32x4){bflo(kw.z), bfhi(kw.z), bflo(kw.w), bfhi(kw.w)}, (f32x4*)(ko + 4));
;         __builtin_nontemporal_store((f32x4){bflo(vw.x), bfhi(vw.x), bflo(vw.y), bfhi(vw.y)}, (f32x4*)vo); __builtin_nontemporal_store((f32x4){bflo(vw.z), bfhi(vw.z), bflo(vw.w), bfhi(vw.w)}, (f32x4*)(vo + 4)); }
; }
; __device__ __forceinline__ void prompt_unit_sb(const Args& a, int l, int b, int h, int qb, LAS unsigned char* lds) {
;     ...
;     const lds_cptr vp0 = (lds_cptr)lds + B_V + ((lane >> 4) & 1) * 32 + (lane & 3) * 8 + (4 * hi + ((lane & 15) >> 2)) * 64;
;     const int qlim = 32 * (wid & 1) + r32;
;     LAS float* wsf = (LAS float*)(lds + B_WSF) + wid * 64;
;     LAS unsigned* flags = (LAS unsigned*)(lds + B_FLAG);
;     FoxState st; st.m = 0.f; st.l = 0.f; st.mq = (bf16x8){}; st.o[0] = (f32x16){}; st.o[1] = (f32x16){};
;     float R = 0.f; bool done = false;
;     { ConvRegs cv; conv_load(cv, a, rowb + q0 + wid * 32, col, lane); conv_store<1>(cv, a, l, h, rowb + q0 + wid * 32, lane); }
;     for (int it = 0; ; ++it) {
	v_lshlrev_b32_e32 v40, 16, v6
	v_and_b32_e32 v41, 0xffff0000, v6
	v_lshlrev_b32_e32 v42, 16, v7
	v_and_b32_e32 v43, 0xffff0000, v7
	v_lshlrev_b32_e32 v6, 16, v8
	v_and_b32_e32 v7, 0xffff0000, v8
	v_lshlrev_b32_e32 v8, 16, v9
	v_and_b32_e32 v9, 0xffff0000, v9
	global_store_dwordx4 v[50:51], v[6:9], off offset:128
	global_store_dwordx4 v[50:51], v[40:43], off
	s_add_i32 s1, s1, 0
	v_lshlrev_b32_e32 v6, 16, v10
	v_and_b32_e32 v7, 0xffff0000, v10
	v_lshlrev_b32_e32 v8, 16, v11
	v_and_b32_e32 v9, 0xffff0000, v11
	global_store_dwordx4 v[52:53], v[6:9], off
	v_cmp_lt_u32_e64 s[10:11], v58, v3
	v_cmp_lt_u32_e64 s[14:15], v57, v3
	v_lshlrev_b32_e32 v6, 16, v12
	v_and_b32_e32 v7, 0xffff0000, v12
	v_lshlrev_b32_e32 v8, 16, v13
	v_and_b32_e32 v9, 0xffff0000, v13
	global_store_dwordx4 v[52:53], v[6:9], off offset:128
	v_cmp_lt_u32_e64 s[18:19], v62, v3
	v_cmp_lt_u32_e64 s[22:23], v61, v3
	v_lshl_add_u64 v[6:7], s[6:7], 0, v[44:45]
	v_lshl_add_u64 v[6:7], v[6:7], 0, s[92:93]
	v_lshl_add_u64 v[10:11], v[6:7], 0, v[4:5]
	v_lshl_add_u64 v[6:7], s[8:9], 0, v[44:45]
	v_lshl_add_u64 v[6:7], v[6:7], 0, s[92:93]
	v_lshl_add_u64 v[12:13], v[6:7], 0, v[4:5]
	v_lshlrev_b32_e32 v6, 16, v14
	v_and_b32_e32 v7, 0xffff0000, v14
	v_lshlrev_b32_e32 v8, 16, v15
	v_and_b32_e32 v9, 0xffff0000, v15
	global_store_dwordx4 v[10:11], v[6:9], off
	v_cmp_lt_u32_e64 s[26:27], v66, v3
	v_cmp_lt_u32_e64 s[30:31], v65, v3
	v_lshlrev_b32_e32 v6, 16, v16
	v_and_b32_e32 v7, 0xffff0000, v16
	v_lshlrev_b32_e32 v8, 16, v17
	v_and_b32_e32 v9, 0xffff0000, v17
	global_store_dwordx4 v[10:11], v[6:9], off offset:128
	v_mov_b32_e32 v16, v5
	v_mov_b32_e32 v17, v5
	v_lshlrev_b32_e32 v6, 16, v20
	v_and_b32_e32 v7, 0xffff0000, v20
	v_lshlrev_b32_e32 v8, 16, v21
	v_and_b32_e32 v9, 0xffff0000, v21
	global_store_dwordx4 v[12:13], v[6:9], off
	v_and_or_b32 v20, v183, 64, v169
	v_cmp_lt_u32_e64 s[36:37], v69, v3
	v_lshlrev_b32_e32 v6, 16, v22
	v_and_b32_e32 v7, 0xffff0000, v22
	v_lshlrev_b32_e32 v8, 16, v23
	v_and_b32_e32 v9, 0xffff0000, v23
	global_store_dwordx4 v[12:13], v[6:9], off offset:128
	v_cmp_lt_u32_e64 s[40:41], v56, v3
	v_cmp_lt_u32_e64 s[44:45], v60, v3
	v_lshl_add_u64 v[6:7], s[6:7], 0, v[46:47]
	v_lshl_add_u64 v[6:7], v[6:7], 0, s[92:93]
	v_lshl_add_u64 v[10:11], v[6:7], 0, v[4:5]
	v_lshl_add_u64 v[6:7], s[8:9], 0, v[46:47]
	v_lshl_add_u64 v[6:7], v[6:7], 0, s[92:93]
	v_lshl_add_u64 v[12:13], v[6:7], 0, v[4:5]
	v_lshlrev_b32_e32 v6, 16, v24
	v_and_b32_e32 v7, 0xffff0000, v24
	v_lshlrev_b32_e32 v8, 16, v25
	v_and_b32_e32 v9, 0xffff0000, v25
	global_store_dwordx4 v[10:11], v[6:9], off
	v_cmp_lt_u32_e64 s[48:49], v59, v3
	v_cmp_lt_u32_e64 s[52:53], v64, v3
	v_lshlrev_b32_e32 v6, 16, v26
	v_and_b32_e32 v7, 0xffff0000, v26
	v_lshlrev_b32_e32 v8, 16, v27
	v_and_b32_e32 v9, 0xffff0000, v27
	global_store_dwordx4 v[10:11], v[6:9], off offset:128
	v_cmp_lt_u32_e64 s[56:57], v63, v3
	v_cmp_lt_u32_e64 s[60:61], v68, v3
	v_lshlrev_b32_e32 v6, 16, v28
	v_and_b32_e32 v7, 0xffff0000, v28
	v_lshlrev_b32_e32 v8, 16, v29
	v_and_b32_e32 v9, 0xffff0000, v29
	global_store_dwordx4 v[12:13], v[6:9], off
	v_cmp_lt_u32_e64 s[64:65], v67, v3
	v_cmp_lt_u32_e64 s[68:69], v70, v3
	v_lshlrev_b32_e32 v6, 16, v30
	v_and_b32_e32 v7, 0xffff0000, v30
	v_lshlrev_b32_e32 v8, 16, v31
	v_and_b32_e32 v9, 0xffff0000, v31
	global_store_dwordx4 v[12:13], v[6:9], off offset:128
	v_cmp_eq_u32_e64 s[72:73], 0, v2
	s_lshl_b32 s5, s3, 15
	v_lshl_add_u64 v[6:7], s[6:7], 0, v[48:49]
	v_lshl_add_u64 v[6:7], v[6:7], 0, s[92:93]
	v_lshl_add_u64 v[10:11], v[6:7], 0, v[4:5]
	v_lshl_add_u64 v[6:7], s[8:9], 0, v[48:49]
	v_lshl_add_u64 v[6:7], v[6:7], 0, s[92:93]
	v_lshl_add_u64 v[12:13], v[6:7], 0, v[4:5]
	v_lshlrev_b32_e32 v4, 4, v169
	v_add3_u32 v172, 0, v171, v4
	v_or_b32_e32 v4, 32, v55
	v_cmp_lt_u32_e64 s[8:9], v4, v3
	v_or_b32_e32 v4, 33, v55
	v_cmp_lt_u32_e64 s[12:13], v4, v3
	v_or_b32_e32 v4, 34, v55
	v_cmp_lt_u32_e64 s[16:17], v4, v3
	v_or_b32_e32 v4, 35, v55
	v_cmp_lt_u32_e64 s[20:21], v4, v3
	v_or_b32_e32 v4, 40, v55
	v_cmp_lt_u32_e64 s[24:25], v4, v3
	v_or_b32_e32 v4, 41, v55
	v_cmp_lt_u32_e64 s[28:29], v4, v3
	v_or_b32_e32 v4, 42, v55
	v_cmp_lt_u32_e64 s[34:35], v4, v3
	v_or_b32_e32 v4, 43, v55
	v_cmp_lt_u32_e64 s[38:39], v4, v3
	v_or_b32_e32 v4, 48, v55
	v_cmp_lt_u32_e64 s[42:43], v4, v3
	v_or_b32_e32 v4, 49, v55
	v_cmp_lt_u32_e64 s[46:47], v4, v3
	v_or_b32_e32 v4, 50, v55
	v_cmp_lt_u32_e64 s[50:51], v4, v3
	v_or_b32_e32 v4, 51, v55
	v_lshlrev_b32_e32 v6, 16, v32
	v_and_b32_e32 v7, 0xffff0000, v32
	v_lshlrev_b32_e32 v8, 16, v33
	v_and_b32_e32 v9, 0xffff0000, v33
	v_cmp_lt_u32_e64 s[54:55], v4, v3
	v_or_b32_e32 v4, 56, v55
	global_store_dwordx4 v[10:11], v[6:9], off
	v_cmp_lt_u32_e64 s[58:59], v4, v3
	v_or_b32_e32 v4, 57, v55
	v_lshlrev_b32_e32 v6, 16, v34
	v_and_b32_e32 v7, 0xffff0000, v34
	v_lshlrev_b32_e32 v8, 16, v35
	v_and_b32_e32 v9, 0xffff0000, v35
	global_store_dwordx4 v[10:11], v[6:9], off offset:128
	v_cmp_lt_u32_e64 s[62:63], v4, v3
	v_or_b32_e32 v4, 58, v55
	v_lshlrev_b32_e32 v6, 16, v36
	v_and_b32_e32 v7, 0xffff0000, v36
	v_lshlrev_b32_e32 v8, 16, v37
	v_and_b32_e32 v9, 0xffff0000, v37
	global_store_dwordx4 v[12:13], v[6:9], off
	v_cmp_lt_u32_e64 s[66:67], v4, v3
	v_or_b32_e32 v4, 59, v55
	v_lshlrev_b32_e32 v6, 16, v38
	v_and_b32_e32 v7, 0xffff0000, v38
	v_lshlrev_b32_e32 v8, 16, v39
	v_and_b32_e32 v9, 0xffff0000, v39
	global_store_dwordx4 v[12:13], v[6:9], off offset:128
	v_cmp_lt_u32_e64 s[6:7], v55, v3
	v_cmp_lt_u32_e64 s[70:71], v4, v3
	s_lshl_b32 s3, s3, 2
	v_mov_b32_e32 v2, v5
	v_mov_b32_e32 v3, v5
	v_mov_b32_e32 v4, v5
	v_mov_b32_e32 v6, v5
	v_mov_b32_e32 v7, v5
	v_mov_b32_e32 v8, v5
	v_mov_b32_e32 v9, v5
	v_mov_b32_e32 v10, v5
	v_mov_b32_e32 v11, v5
	v_mov_b32_e32 v12, v5
	v_mov_b32_e32 v13, v5
	v_mov_b32_e32 v14, v5
	v_mov_b32_e32 v15, v5
	v_lshlrev_b32_e32 v173, 2, v20
	v_mov_b64_e32 v[34:35], v[16:17]
	v_mov_b64_e32 v[50:51], v[16:17]
	s_add_i32 s1, s1, 0x20c00
	s_mov_b32 s85, 0
	s_lshl_b32 s93, s4, 13
	s_sub_i32 s94, 0x30000, s5
	s_sub_i32 s95, s4, s3
	s_sub_i32 s33, 0, s3
	v_mov_b32_e32 v52, 0
	s_mov_b64 s[74:75], 0
	v_mov_b64_e32 v[32:33], v[14:15]
	v_mov_b64_e32 v[30:31], v[12:13]
	v_mov_b64_e32 v[28:29], v[10:11]
	v_mov_b64_e32 v[26:27], v[8:9]
	v_mov_b64_e32 v[24:25], v[6:7]
	v_mov_b64_e32 v[22:23], v[4:5]
	v_mov_b64_e32 v[20:21], v[2:3]
	v_mov_b64_e32 v[48:49], v[14:15]
	v_mov_b64_e32 v[46:47], v[12:13]
	v_mov_b64_e32 v[44:45], v[10:11]
	v_mov_b64_e32 v[42:43], v[8:9]
	v_mov_b64_e32 v[40:41], v[6:7]
	v_mov_b64_e32 v[38:39], v[4:5]
	v_mov_b64_e32 v[36:37], v[2:3]
	s_mov_b32 s3, 28
	s_branch .LBB0_270

; #define ATT_WAIT_BAR() asm volatile("s_waitcnt vmcnt(0) lgkmcnt(0)\n\ts_barrier" ::: "memory")
; __device__ __forceinline__ void prompt_unit_fox(const Args& a, int l, int b, int h, int qb, LAS unsigned char* lds) {
;     ...
;         ATT_WAIT_BAR();
;         if (jp >= 1) ATT_DMA2(jp - 1, slot == 2 ? 0 : slot + 1);
.LBB0_312:
	s_waitcnt vmcnt(0) lgkmcnt(0)
	s_barrier
	s_cmp_lg_u32 s90, 0
	s_cbranch_scc0 .LBB0_343
	s_add_i32 s80, s90, -1
	s_mov_b32 s81, s87
	s_lshl_b32 s3, s75, 14
	s_lshl_b64 s[80:81], s[80:81], 18
	s_add_i32 s33, s3, 0x4000
	s_cmp_lg_u32 s75, 2
	s_cselect_b32 s33, s33, 0
	v_lshl_add_u64 v[20:21], v[176:177], 0, s[80:81]
	s_add_i32 s82, s79, s33
	s_mov_b32 s83, m0
	s_mov_b32 m0, s82
	s_nop 0
	global_load_lds_dwordx4 v[20:21], off
	s_mov_b32 m0, s83
	s_mov_b64 s[96:97], 0x20000
	v_lshl_add_u64 v[20:21], v[20:21], 0, s[96:97]
	s_add_i32 s82, s84, s33
	s_mov_b32 s83, m0
	s_mov_b32 m0, s82
	s_nop 0
	global_load_lds_dwordx4 v[20:21], off
	s_mov_b32 m0, s83
	v_lshl_add_u64 v[20:21], v[178:179], 0, s[80:81]
	s_add_i32 s80, s85, s33
	s_mov_b32 s81, m0
	s_mov_b32 m0, s80
	s_nop 0
	global_load_lds_dwordx4 v[20:21], off
	s_mov_b32 m0, s81
	v_lshl_add_u64 v[20:21], v[20:21], 0, s[96:97]
	s_add_i32 s33, s76, s33
	s_mov_b32 s80, m0
	s_mov_b32 m0, s33
	s_nop 0
	global_load_lds_dwordx4 v[20:21], off
	s_mov_b32 m0, s80
	s_cbranch_execnz .LBB0_315

; __device__ __forceinline__ void vfrags(VFrags& v, lds_cptr vp) {
; #pragma unroll
;     ...
; }
; __device__ __forceinline__ void pv(f32x16 (&o)[2], const VFrags& v, const u32x4& pw0, const u32x4& pw1, const u32x4& pw2, const u32x4& pw3) {
;     ...
;     o[0] = __builtin_amdgcn_mfma_f32_32x32x16_bf16(__builtin_bit_cast(bf16x8, pw0), ATT_VF(0), o[0], 0, 0, 0);
;     o[1] = __builtin_amdgcn_mfma_f32_32x32x16_bf16(__builtin_bit_cast(bf16x8, pw0), ATT_VF(4), o[1], 0, 0, 0);
;     o[0] = __builtin_amdgcn_mfma_f32_32x32x16_bf16(__builtin_bit_cast(bf16x8, pw1), ATT_VF(1), o[0], 0, 0, 0);
;     o[1] = __builtin_amdgcn_mfma_f32_32x32x16_bf16(__builtin_bit_cast(bf16x8, pw1), ATT_VF(5), o[1], 0, 0, 0);
;     o[0] = __builtin_amdgcn_mfma_f32_32x32x16_bf16(__builtin_bit_cast(bf16x8, pw2), ATT_VF(2), o[0], 0, 0, 0);
;     o[1] = __builtin_amdgcn_mfma_f32_32x32x16_bf16(__builtin_bit_cast(bf16x8, pw2), ATT_VF(6), o[1], 0, 0, 0);
;     o[0] = __builtin_amdgcn_mfma_f32_32x32x16_bf16(__builtin_bit_cast(bf16x8, pw3), ATT_VF(3), o[0], 0, 0, 0);
;     o[1] = __builtin_amdgcn_mfma_f32_32x32x16_bf16(__builtin_bit_cast(bf16x8, pw3), ATT_VF(7), o[1], 0, 0, 0);
;     ...
; }
; __device__ __forceinline__ void fox_pair_pv(FoxState& st, const PairP& pp, lds_cptr vpB) {
;     { VFrags vf; vfrags(vf, vpB + 8192); pv(st.o, vf, pp.w[0], pp.w[1], pp.w[2], pp.w[3]); }
;     { VFrags vf; vfrags(vf, vpB); pv(st.o, vf, pp.w[4], pp.w[5], pp.w[6], pp.w[7]); }
; }
.LBB0_315:
	s_andn2_b64 vcc, exec, s[4:5]
	s_cbranch_vccnz .LBB0_317
	v_lshl_add_u32 v3, s1, 14, v180
	ds_read_b64_tr_b16 v[20:21], v3 offset:57344
	ds_read_b64_tr_b16 v[22:23], v3 offset:57856
	ds_read_b64_tr_b16 v[24:25], v3 offset:58368
	ds_read_b64_tr_b16 v[26:27], v3 offset:58880
	s_waitcnt lgkmcnt(2)
	v_mfma_f32_32x32x16_bf16 v[68:83], v[152:155], v[20:23], v[68:83]
	ds_read_b64_tr_b16 v[20:21], v3 offset:61440
	ds_read_b64_tr_b16 v[22:23], v3 offset:61952
	ds_read_b64_tr_b16 v[28:29], v3 offset:62464
	ds_read_b64_tr_b16 v[30:31], v3 offset:62976
	s_waitcnt lgkmcnt(2)
	v_mfma_f32_32x32x16_bf16 v[52:67], v[152:155], v[20:23], v[52:67]
	v_mfma_f32_32x32x16_bf16 v[68:83], v[148:151], v[24:27], v[68:83]
	ds_read_b64_tr_b16 v[20:21], v3 offset:59392
	ds_read_b64_tr_b16 v[22:23], v3 offset:59904
	ds_read_b64_tr_b16 v[24:25], v3 offset:60416
	ds_read_b64_tr_b16 v[26:27], v3 offset:60928
	s_waitcnt lgkmcnt(4)
	v_mfma_f32_32x32x16_bf16 v[52:67], v[148:151], v[28:31], v[52:67]
	s_waitcnt lgkmcnt(2)
	v_mfma_f32_32x32x16_bf16 v[68:83], v[144:147], v[20:23], v[68:83]
	ds_read_b64_tr_b16 v[20:21], v3 offset:63488
	ds_read_b64_tr_b16 v[22:23], v3 offset:64000
	ds_read_b64_tr_b16 v[28:29], v3 offset:64512
	ds_read_b64_tr_b16 v[30:31], v3 offset:65024
	s_waitcnt lgkmcnt(2)
	v_mfma_f32_32x32x16_bf16 v[52:67], v[144:147], v[20:23], v[52:67]
	v_mfma_f32_32x32x16_bf16 v[68:83], v[140:143], v[24:27], v[68:83]
	ds_read_b64_tr_b16 v[20:21], v3 offset:49152
	ds_read_b64_tr_b16 v[22:23], v3 offset:49664
	ds_read_b64_tr_b16 v[24:25], v3 offset:50176
	ds_read_b64_tr_b16 v[26:27], v3 offset:50688
	s_waitcnt lgkmcnt(4)
	v_mfma_f32_32x32x16_bf16 v[52:67], v[140:143], v[28:31], v[52:67]
	s_waitcnt lgkmcnt(2)
	v_mfma_f32_32x32x16_bf16 v[68:83], v[136:139], v[20:23], v[68:83]
	ds_read_b64_tr_b16 v[20:21], v3 offset:53248
	ds_read_b64_tr_b16 v[22:23], v3 offset:53760
	ds_read_b64_tr_b16 v[28:29], v3 offset:54272
	ds_read_b64_tr_b16 v[30:31], v3 offset:54784
	s_waitcnt lgkmcnt(2)
	v_mfma_f32_32x32x16_bf16 v[52:67], v[136:139], v[20:23], v[52:67]
	v_mfma_f32_32x32x16_bf16 v[68:83], v[132:135], v[24:27], v[68:83]
	ds_read_b64_tr_b16 v[20:21], v3 offset:51200
	ds_read_b64_tr_b16 v[22:23], v3 offset:51712
	ds_read_b64_tr_b16 v[24:25], v3 offset:52224
	ds_read_b64_tr_b16 v[26:27], v3 offset:52736
	s_waitcnt lgkmcnt(4)
	v_mfma_f32_32x32x16_bf16 v[52:67], v[132:135], v[28:31], v[52:67]
	s_waitcnt lgkmcnt(2)
	v_mfma_f32_32x32x16_bf16 v[68:83], v[128:131], v[20:23], v[68:83]
	ds_read_b64_tr_b16 v[20:21], v3 offset:55296
	ds_read_b64_tr_b16 v[22:23], v3 offset:55808
	ds_read_b64_tr_b16 v[36:37], v3 offset:56320
	ds_read_b64_tr_b16 v[38:39], v3 offset:56832
	s_waitcnt lgkmcnt(2)
	v_mfma_f32_32x32x16_bf16 v[52:67], v[128:131], v[20:23], v[52:67]
	v_mfma_f32_32x32x16_bf16 v[68:83], v[124:127], v[24:27], v[68:83]
	s_waitcnt lgkmcnt(0)
	v_mfma_f32_32x32x16_bf16 v[52:67], v[124:127], v[36:39], v[52:67]

; #define LAS __attribute__((address_space(3)))
; __device__ __forceinline__ bool fox_pair_qs(FoxState& st, PairP& pp, lds_cptr kslotB, const bf16x8 (&qr)[4], const LAS u32x2* augB  , bool careful, int r32, int hi, LAS float* wsf) {
;     bf16x8 kfA[8], kfB[8]; kfrags(kfA, kslotB + 8192, r32, hi); kfrags(kfB, kslotB, r32, hi);
;     const u32x2 t0 = augB[64], t1 = augB[96], t2 = augB[0], t3 = augB[32];
;     const f32x16 zz = {};
;     f32x16 a0, a1, b0, b1;
;     a0 = __builtin_amdgcn_mfma_f32_32x32x16_bf16(__builtin_bit_cast(bf16x8, (u32x4){t0.x, t0.y, 0xBF80BF80u, 0u}), st.mq, zz, 0, 0, 0);
;     a1 = __builtin_amdgcn_mfma_f32_32x32x16_bf16(__builtin_bit_cast(bf16x8, (u32x4){t1.x, t1.y, 0xBF80BF80u, 0u}), st.mq, zz, 0, 0, 0);
;     b0 = __builtin_amdgcn_mfma_f32_32x32x16_bf16(__builtin_bit_cast(bf16x8, (u32x4){t2.x, t2.y, 0xBF80BF80u, 0u}), st.mq, zz, 0, 0, 0);
;     b1 = __builtin_amdgcn_mfma_f32_32x32x16_bf16(__builtin_bit_cast(bf16x8, (u32x4){t3.x, t3.y, 0xBF80BF80u, 0u}), st.mq, zz, 0, 0, 0);
; #pragma unroll
;     for (int d0 = 0; d0 < 4; ++d0) {
;         a0 = __builtin_amdgcn_mfma_f32_32x32x16_bf16(kfA[2 * d0], qr[d0], a0, 0, 0, 0); a1 = __builtin_amdgcn_mfma_f32_32x32x16_bf16(kfA[2 * d0 + 1], qr[d0], a1, 0, 0, 0);
;         b0 = __builtin_amdgcn_mfma_f32_32x32x16_bf16(kfB[2 * d0], qr[d0], b0, 0, 0, 0); b1 = __builtin_amdgcn_mfma_f32_32x32x16_bf16(kfB[2 * d0 + 1], qr[d0], b1, 0, 0, 0);
;     }
.LBB0_330:
	ds_read2_b64 v[52:55], v124 offset0:64 offset1:96
	v_mov_b64_e32 v[56:57], s[84:85]
	v_mov_b64_e32 v[58:59], s[86:87]
	ds_read_b128 v[126:129], v125 offset:8192
	ds_read2_b64 v[66:69], v124 offset1:32
	s_waitcnt lgkmcnt(2)
	v_mov_b32_e32 v56, v52
	v_mov_b32_e32 v57, v53
	v_mov_b64_e32 v[70:71], s[84:85]
	v_mov_b64_e32 v[72:73], s[86:87]
	s_waitcnt lgkmcnt(0)
	v_mov_b32_e32 v70, v68
	v_mfma_f32_32x32x16_bf16 v[84:99], v[56:59], v[160:163], 0
	v_mov_b64_e32 v[56:57], s[84:85]
	v_mov_b64_e32 v[58:59], s[86:87]
	v_mov_b32_e32 v56, v54
	v_mov_b32_e32 v57, v55
	v_mov_b64_e32 v[52:53], s[84:85]
	v_mov_b64_e32 v[54:55], s[86:87]
	v_mov_b32_e32 v52, v66
	v_mfma_f32_32x32x16_bf16 v[84:99], v[126:129], v[6:9], v[84:99]
	ds_read_b128 v[126:129], v125 offset:8704
	v_mov_b32_e32 v53, v67
	v_mov_b32_e32 v71, v69
	s_xor_b64 s[4:5], s[82:83], -1
	s_and_b64 vcc, exec, s[4:5]
	v_mfma_f32_32x32x16_bf16 v[100:115], v[56:59], v[160:163], 0
	s_waitcnt lgkmcnt(0)
	v_mfma_f32_32x32x16_bf16 v[100:115], v[126:129], v[6:9], v[100:115]
	ds_read_b128 v[126:129], v125
	v_mfma_f32_32x32x16_bf16 v[52:67], v[52:55], v[160:163], 0
	s_waitcnt lgkmcnt(0)
	v_mfma_f32_32x32x16_bf16 v[52:67], v[126:129], v[6:9], v[52:67]
	ds_read_b128 v[126:129], v125 offset:512
	v_mfma_f32_32x32x16_bf16 v[68:83], v[70:73], v[160:163], 0
	s_waitcnt lgkmcnt(0)
	v_mfma_f32_32x32x16_bf16 v[68:83], v[126:129], v[6:9], v[68:83]
	ds_read_b128 v[126:129], v125 offset:10240
	s_waitcnt lgkmcnt(0)
	v_mfma_f32_32x32x16_bf16 v[84:99], v[126:129], v[10:13], v[84:99]
	ds_read_b128 v[126:129], v125 offset:10752
	s_waitcnt lgkmcnt(0)
	v_mfma_f32_32x32x16_bf16 v[100:115], v[126:129], v[10:13], v[100:115]
	ds_read_b128 v[126:129], v125 offset:2048
	s_waitcnt lgkmcnt(0)
	v_mfma_f32_32x32x16_bf16 v[52:67], v[126:129], v[10:13], v[52:67]
	ds_read_b128 v[126:129], v125 offset:2560
	s_waitcnt lgkmcnt(0)
	v_mfma_f32_32x32x16_bf16 v[68:83], v[126:129], v[10:13], v[68:83]
	ds_read_b128 v[126:129], v125 offset:12288
	s_waitcnt lgkmcnt(0)
	v_mfma_f32_32x32x16_bf16 v[84:99], v[126:129], v[14:17], v[84:99]
	ds_read_b128 v[126:129], v125 offset:12800
	s_waitcnt lgkmcnt(0)
	v_mfma_f32_32x32x16_bf16 v[100:115], v[126:129], v[14:17], v[100:115]
	ds_read_b128 v[126:129], v125 offset:4096
	s_waitcnt lgkmcnt(0)
	v_mfma_f32_32x32x16_bf16 v[52:67], v[126:129], v[14:17], v[52:67]
	ds_read_b128 v[126:129], v125 offset:4608
	s_waitcnt lgkmcnt(0)
	v_mfma_f32_32x32x16_bf16 v[68:83], v[126:129], v[14:17], v[68:83]
	ds_read_b128 v[126:129], v125 offset:14336
	s_waitcnt lgkmcnt(0)
	v_mfma_f32_32x32x16_bf16 v[84:99], v[126:129], v[116:119], v[84:99]
	ds_read_b128 v[126:129], v125 offset:14848
	s_waitcnt lgkmcnt(0)
	v_mfma_f32_32x32x16_bf16 v[100:115], v[126:129], v[116:119], v[100:115]
	ds_read_b128 v[126:129], v125 offset:6144
	s_waitcnt lgkmcnt(0)
	v_mfma_f32_32x32x16_bf16 v[52:67], v[126:129], v[116:119], v[52:67]
	ds_read_b128 v[126:129], v125 offset:6656
	s_waitcnt lgkmcnt(0)
	v_mfma_f32_32x32x16_bf16 v[68:83], v[126:129], v[116:119], v[68:83]
	s_cbranch_vccnz .LBB0_334
; #define LAS __attribute__((address_space(3)))
; __device__ __forceinline__ float swap_max(float m) { auto rr = __builtin_amdgcn_permlane32_swap(__float_as_uint(m), __float_as_uint(m), false, false); return fmaxf(__uint_as_float(rr[0]), __uint_as_float(rr[1])); }
; __device__ __forceinline__ float max3f(float a, float b, float c) { return __builtin_fmaxf(__builtin_fmaxf(a, b), c); }
; #define ATT_LDS_WAIT() asm volatile("s_waitcnt lgkmcnt(0)" ::: "memory")
; __device__ __forceinline__ bool fox_pair_qs(FoxState& st, PairP& pp, lds_cptr kslotB, const bf16x8 (&qr)[4], const LAS u32x2* augB  , bool careful, int r32, int hi, LAS float* wsf) {
;     ...
;     if (careful) {
;         asm volatile("; careful pass: move the reference" ::: "memory");
;         float rm = max3f(a0[0], a1[0], b0[0]), rm2 = max3f(b1[0], a0[1], a1[1]);
;         rm = max3f(rm, b0[1], b1[1]);
; #pragma unroll
;         for (int r = 2; r < 16; ++r) { rm = max3f(rm, a0[r], a1[r]); rm2 = max3f(rm2, b0[r], b1[r]); }
;         rm = swap_max(max3f(rm, rm2, rm2));
;         const float dl = fmaxf(rm, 0.f);
;         st.m += dl; st.mq = make_mq(st.m, hi);
; #pragma unroll
;         for (int r = 0; r < 16; ++r) { a0[r] -= dl; a1[r] -= dl; b0[r] -= dl; b1[r] -= dl; }
;         const float f = __builtin_amdgcn_exp2f(-dl);
;         st.l *= f;
;         if (hi == 0) wsf[r32] = f;
;         ATT_LDS_WAIT();
; #pragma unroll
;         for (int g = 0; g < 4; ++g) { const f32x4 fv = *(const LAS f32x4*)(wsf + 8 * g + 4 * hi);
; #pragma unroll
;             for (int i = 0; i < 4; ++i) { st.o[0][4 * g + i] *= fv[i]; st.o[1][4 * g + i] *= fv[i]; } }
;     }
	s_nop 4
	v_max_f32_e32 v3, v100, v100
	v_max_f32_e32 v4, v84, v84
	v_max_f32_e32 v3, v4, v3
	s_nop 2
	v_max3_f32 v4, v68, v85, v101
	v_max3_f32 v3, v3, v52, v53
	v_max3_f32 v3, v3, v69, v86
	v_max3_f32 v4, v4, v54, v70
	v_max3_f32 v3, v3, v102, v87
	v_max3_f32 v4, v4, v55, v71
	v_max3_f32 v3, v3, v103, v88
	v_max3_f32 v4, v4, v56, v72
	v_max3_f32 v3, v3, v104, v89
	v_max3_f32 v4, v4, v57, v73
	v_max3_f32 v3, v3, v105, v90
	v_max3_f32 v4, v4, v58, v74
	v_max3_f32 v3, v3, v106, v91
	v_max3_f32 v4, v4, v59, v75
	v_max3_f32 v3, v3, v107, v92
	v_max3_f32 v4, v4, v60, v76
	v_max3_f32 v3, v3, v108, v93
	v_max3_f32 v4, v4, v61, v77
	v_max3_f32 v3, v3, v109, v94
	v_max3_f32 v4, v4, v62, v78
	v_max3_f32 v3, v3, v110, v95
	v_max3_f32 v4, v4, v63, v79
	v_max3_f32 v3, v3, v111, v96
	v_max3_f32 v4, v4, v64, v80
	v_max3_f32 v3, v3, v112, v97
	v_max3_f32 v4, v4, v65, v81
	v_max3_f32 v3, v3, v113, v98
	v_max3_f32 v4, v4, v66, v82
	v_max3_f32 v3, v3, v114, v99
	v_max3_f32 v4, v4, v67, v83
	v_max3_f32 v3, v3, v115, v4
	v_mov_b32_e32 v4, v3
	s_nop 1
	v_permlane32_swap_b32_e32 v3, v4
	v_max3_f32 v126, v3, v4, 0
	v_exp_f32_e64 v127, -v126
	s_and_saveexec_b64 vcc, s[6:7]
	ds_write_b32 v182, v127
	s_or_b64 exec, exec, vcc
	v_add_f32_e32 v191, v191, v126
	v_cvt_pk_bf16_f32 v3, v191, 0
	v_lshlrev_b32_e32 v3, 16, v3
	v_sub_f32_e32 v4, v191, v3
	v_cvt_pk_bf16_f32 v128, v4, 0
	v_lshlrev_b32_e32 v128, 16, v128
	v_sub_f32_e32 v4, v4, v128
	s_waitcnt lgkmcnt(0)
	v_add_u32_e32 v138, s78, v172
	v_cvt_pk_bf16_f32 v4, v128, v4
	v_sub_f32_e32 v99, v99, v126
	v_sub_f32_e32 v98, v98, v126
	v_sub_f32_e32 v97, v97, v126
	v_sub_f32_e32 v96, v96, v126
	v_sub_f32_e32 v95, v95, v126
	v_sub_f32_e32 v94, v94, v126
	v_sub_f32_e32 v93, v93, v126
	v_sub_f32_e32 v92, v92, v126
	v_sub_f32_e32 v91, v91, v126
	v_sub_f32_e32 v90, v90, v126
	v_sub_f32_e32 v89, v89, v126
	v_sub_f32_e32 v88, v88, v126
	v_sub_f32_e32 v87, v87, v126
	v_sub_f32_e32 v86, v86, v126
	v_sub_f32_e32 v85, v85, v126
	v_sub_f32_e32 v84, v84, v126
	v_sub_f32_e32 v115, v115, v126
	v_sub_f32_e32 v114, v114, v126
	v_sub_f32_e32 v113, v113, v126
	v_sub_f32_e32 v112, v112, v126
	v_sub_f32_e32 v111, v111, v126
	v_sub_f32_e32 v110, v110, v126
	v_sub_f32_e32 v109, v109, v126
	v_sub_f32_e32 v108, v108, v126
	v_sub_f32_e32 v107, v107, v126
	v_sub_f32_e32 v106, v106, v126
	v_sub_f32_e32 v105, v105, v126
	v_sub_f32_e32 v104, v104, v126
	v_sub_f32_e32 v103, v103, v126
	v_sub_f32_e32 v102, v102, v126
	v_sub_f32_e32 v101, v101, v126
	v_sub_f32_e32 v100, v100, v126
	v_sub_f32_e32 v67, v67, v126
	v_sub_f32_e32 v66, v66, v126
	v_sub_f32_e32 v65, v65, v126
	v_sub_f32_e32 v64, v64, v126
	v_sub_f32_e32 v63, v63, v126
	v_sub_f32_e32 v62, v62, v126
	v_sub_f32_e32 v61, v61, v126
	v_sub_f32_e32 v60, v60, v126
	v_sub_f32_e32 v59, v59, v126
	v_sub_f32_e32 v58, v58, v126
	v_sub_f32_e32 v57, v57, v126
	v_sub_f32_e32 v56, v56, v126
	v_sub_f32_e32 v55, v55, v126
	v_sub_f32_e32 v54, v54, v126
	v_sub_f32_e32 v53, v53, v126
	v_sub_f32_e32 v52, v52, v126
	v_sub_f32_e32 v83, v83, v126
	v_sub_f32_e32 v82, v82, v126
	v_sub_f32_e32 v81, v81, v126
	v_sub_f32_e32 v80, v80, v126
	v_sub_f32_e32 v79, v79, v126
	v_sub_f32_e32 v78, v78, v126
	v_sub_f32_e32 v77, v77, v126
	v_sub_f32_e32 v76, v76, v126
	v_sub_f32_e32 v75, v75, v126
	v_sub_f32_e32 v74, v74, v126
	v_sub_f32_e32 v73, v73, v126
	v_sub_f32_e32 v72, v72, v126
	v_sub_f32_e32 v71, v71, v126
	v_sub_f32_e32 v70, v70, v126
	v_sub_f32_e32 v69, v69, v126
	v_sub_f32_e32 v68, v68, v126
	v_mul_f32_e32 v194, v194, v127
	ds_read_b128 v[126:129], v138
	ds_read_b128 v[130:133], v138 offset:32
	ds_read_b128 v[134:137], v138 offset:64
	ds_read_b128 v[138:141], v138 offset:96
	v_cvt_pk_bf16_f32 v3, 1.0, v3
	v_cndmask_b32_e64 v4, 0, v4, s[6:7]
	v_cndmask_b32_e64 v3, 0, v3, s[6:7]
	v_mov_b64_e32 v[162:163], v[4:5]
	s_waitcnt lgkmcnt(0)
	v_pk_mul_f32 v[32:33], v[32:33], v[138:139]
	v_pk_mul_f32 v[28:29], v[28:29], v[134:135]
	v_pk_mul_f32 v[24:25], v[24:25], v[130:131]
	v_pk_mul_f32 v[34:35], v[34:35], v[140:141]
	v_pk_mul_f32 v[30:31], v[30:31], v[136:137]
	v_pk_mul_f32 v[26:27], v[26:27], v[132:133]
	v_pk_mul_f32 v[22:23], v[22:23], v[128:129]
	v_pk_mul_f32 v[20:21], v[20:21], v[126:127]
	v_pk_mul_f32 v[48:49], v[48:49], v[138:139]
	v_pk_mul_f32 v[44:45], v[44:45], v[134:135]
	v_pk_mul_f32 v[40:41], v[40:41], v[130:131]
	v_pk_mul_f32 v[50:51], v[50:51], v[140:141]
	v_pk_mul_f32 v[46:47], v[46:47], v[136:137]
	v_pk_mul_f32 v[42:43], v[42:43], v[132:133]
	v_pk_mul_f32 v[38:39], v[38:39], v[128:129]
	v_pk_mul_f32 v[36:37], v[36:37], v[126:127]
	v_mov_b64_e32 v[160:161], v[2:3]

; __device__ __forceinline__ unsigned cvtpk(float lo, float hi) { f32x2 v = {lo, hi}; bf16x2_t b = __builtin_convertvector(v, bf16x2_t); return __builtin_bit_cast(unsigned, b); }
; __device__ __forceinline__ float fadd_s(float a, float b) { float r = a + b; asm volatile("" : "+v"(r)); return r; }
; #define ATT_PACK4(P, B, F) (u32x4){F(P[B], P[B + 1]), F(P[B + 2], P[B + 3]), F(P[B + 4], P[B + 5]), F(P[B + 6], P[B + 7])}
; __device__ __forceinline__ bool fox_pair_qs(FoxState& st, PairP& pp, lds_cptr kslotB, const bf16x8 (&qr)[4], const LAS u32x2* augB  , bool careful, int r32, int hi, LAS float* wsf) {
;     ...
;     float sacc = 0.f, sacc2 = 0.f;
; #pragma unroll
;     for (int r = 0; r < 16; ++r) { a0[r] = __builtin_amdgcn_exp2f(a0[r]); a1[r] = __builtin_amdgcn_exp2f(a1[r]); sacc = fadd_s(sacc, a0[r]); sacc2 = fadd_s(sacc2, a1[r]); }
;     pp.w[0] = ATT_PACK4(a0, 0, cvtpk); pp.w[1] = ATT_PACK4(a0, 8, cvtpk); pp.w[2] = ATT_PACK4(a1, 0, cvtpk); pp.w[3] = ATT_PACK4(a1, 8, cvtpk);
; #pragma unroll
;     for (int r = 0; r < 16; ++r) { b0[r] = __builtin_amdgcn_exp2f(b0[r]); b1[r] = __builtin_amdgcn_exp2f(b1[r]); sacc = fadd_s(sacc, b0[r]); sacc2 = fadd_s(sacc2, b1[r]); }
;     pp.w[4] = ATT_PACK4(b0, 0, cvtpk); pp.w[5] = ATT_PACK4(b0, 8, cvtpk); pp.w[6] = ATT_PACK4(b1, 0, cvtpk); pp.w[7] = ATT_PACK4(b1, 8, cvtpk);
;     const float ts = fadd_s(sacc, sacc2);
;     if (!careful && __any(!(ts < FOX_BIG))) return false;
;     st.l = fadd_s(st.l, ts);
;     return true;
; }
; __device__ __forceinline__ void fox_pair_pv(FoxState& st, const PairP& pp, lds_cptr vpB) {
;     { VFrags vf; vfrags(vf, vpB + 8192); pv(st.o, vf, pp.w[0], pp.w[1], pp.w[2], pp.w[3]); }
;     { VFrags vf; vfrags(vf, vpB); pv(st.o, vf, pp.w[4], pp.w[5], pp.w[6], pp.w[7]); }
; }
.LBB0_341:
	v_cvt_pk_bf16_f32 v152, v84, v100
	v_cvt_pk_bf16_f32 v153, v101, v102
	v_cvt_pk_bf16_f32 v154, v103, v104
	v_cvt_pk_bf16_f32 v155, v105, v106
	v_cvt_pk_bf16_f32 v148, v107, v108
	v_cvt_pk_bf16_f32 v149, v109, v110
	v_cvt_pk_bf16_f32 v150, v111, v112
	v_cvt_pk_bf16_f32 v151, v113, v114
	v_cvt_pk_bf16_f32 v144, v3, v4
	v_cvt_pk_bf16_f32 v145, v85, v86
	v_cvt_pk_bf16_f32 v146, v87, v88
	v_cvt_pk_bf16_f32 v147, v89, v90
	v_cvt_pk_bf16_f32 v140, v91, v92
	v_cvt_pk_bf16_f32 v141, v93, v94
	v_cvt_pk_bf16_f32 v142, v95, v96
	v_cvt_pk_bf16_f32 v143, v97, v98
	v_cvt_pk_bf16_f32 v136, v99, v68
	v_cvt_pk_bf16_f32 v137, v69, v70
	v_cvt_pk_bf16_f32 v138, v71, v72
	v_cvt_pk_bf16_f32 v139, v73, v74
	v_cvt_pk_bf16_f32 v132, v75, v76
	v_cvt_pk_bf16_f32 v133, v77, v78
	v_cvt_pk_bf16_f32 v134, v79, v80
	v_cvt_pk_bf16_f32 v135, v81, v82
	v_cvt_pk_bf16_f32 v128, v52, v53
	v_cvt_pk_bf16_f32 v129, v54, v55
	v_cvt_pk_bf16_f32 v130, v56, v57
	v_cvt_pk_bf16_f32 v131, v58, v59
	v_cvt_pk_bf16_f32 v124, v60, v61
	v_cvt_pk_bf16_f32 v125, v62, v63
	v_cvt_pk_bf16_f32 v126, v64, v65
	v_cvt_pk_bf16_f32 v127, v66, v67
	s_andn2_b64 vcc, exec, s[92:93]
	s_mov_b64 s[4:5], -1
	s_cbranch_vccnz .LBB0_344
	ds_read_b64_tr_b16 v[52:53], v190 offset:57344
	ds_read_b64_tr_b16 v[54:55], v190 offset:57856
	s_mov_b64 s[4:5], 0
	s_waitcnt lgkmcnt(0)
	v_mfma_f32_32x32x16_bf16 v[20:35], v[152:155], v[52:55], v[20:35]
	ds_read_b64_tr_b16 v[52:53], v190 offset:61440
	ds_read_b64_tr_b16 v[54:55], v190 offset:61952
	s_waitcnt lgkmcnt(0)
	v_mfma_f32_32x32x16_bf16 v[36:51], v[152:155], v[52:55], v[36:51]
	ds_read_b64_tr_b16 v[52:53], v190 offset:58368
	ds_read_b64_tr_b16 v[54:55], v190 offset:58880
	s_waitcnt lgkmcnt(0)
	v_mfma_f32_32x32x16_bf16 v[20:35], v[148:151], v[52:55], v[20:35]
	ds_read_b64_tr_b16 v[52:53], v190 offset:62464
	ds_read_b64_tr_b16 v[54:55], v190 offset:62976
	s_waitcnt lgkmcnt(0)
	v_mfma_f32_32x32x16_bf16 v[36:51], v[148:151], v[52:55], v[36:51]
	ds_read_b64_tr_b16 v[52:53], v190 offset:59392
	ds_read_b64_tr_b16 v[54:55], v190 offset:59904
	s_waitcnt lgkmcnt(0)
	v_mfma_f32_32x32x16_bf16 v[20:35], v[144:147], v[52:55], v[20:35]
	ds_read_b64_tr_b16 v[52:53], v190 offset:63488
	ds_read_b64_tr_b16 v[54:55], v190 offset:64000
	s_waitcnt lgkmcnt(0)
	v_mfma_f32_32x32x16_bf16 v[36:51], v[144:147], v[52:55], v[36:51]
	ds_read_b64_tr_b16 v[52:53], v190 offset:60416
	ds_read_b64_tr_b16 v[54:55], v190 offset:60928
	s_waitcnt lgkmcnt(0)
	v_mfma_f32_32x32x16_bf16 v[20:35], v[140:143], v[52:55], v[20:35]
	ds_read_b64_tr_b16 v[52:53], v190 offset:64512
	ds_read_b64_tr_b16 v[54:55], v190 offset:65024
	s_waitcnt lgkmcnt(0)
	v_mfma_f32_32x32x16_bf16 v[36:51], v[140:143], v[52:55], v[36:51]
	ds_read_b64_tr_b16 v[52:53], v190 offset:49152
	ds_read_b64_tr_b16 v[54:55], v190 offset:49664
	s_waitcnt lgkmcnt(0)
	v_mfma_f32_32x32x16_bf16 v[20:35], v[136:139], v[52:55], v[20:35]
	ds_read_b64_tr_b16 v[52:53], v190 offset:53248
	ds_read_b64_tr_b16 v[54:55], v190 offset:53760
	s_waitcnt lgkmcnt(0)
	v_mfma_f32_32x32x16_bf16 v[36:51], v[136:139], v[52:55], v[36:51]
	ds_read_b64_tr_b16 v[52:53], v190 offset:50176
	ds_read_b64_tr_b16 v[54:55], v190 offset:50688
	s_waitcnt lgkmcnt(0)
	v_mfma_f32_32x32x16_bf16 v[20:35], v[132:135], v[52:55], v[20:35]
	ds_read_b64_tr_b16 v[52:53], v190 offset:54272
	ds_read_b64_tr_b16 v[54:55], v190 offset:54784
	s_waitcnt lgkmcnt(0)
	v_mfma_f32_32x32x16_bf16 v[36:51], v[132:135], v[52:55], v[36:51]
	ds_read_b64_tr_b16 v[52:53], v190 offset:51200
	ds_read_b64_tr_b16 v[54:55], v190 offset:51712
	s_waitcnt lgkmcnt(0)
	v_mfma_f32_32x32x16_bf16 v[20:35], v[128:131], v[52:55], v[20:35]
	ds_read_b64_tr_b16 v[52:53], v190 offset:55296
	ds_read_b64_tr_b16 v[54:55], v190 offset:55808
	s_waitcnt lgkmcnt(0)
	v_mfma_f32_32x32x16_bf16 v[36:51], v[128:131], v[52:55], v[36:51]
	ds_read_b64_tr_b16 v[52:53], v190 offset:52224
	ds_read_b64_tr_b16 v[54:55], v190 offset:52736
	s_waitcnt lgkmcnt(0)
	v_mfma_f32_32x32x16_bf16 v[20:35], v[124:127], v[52:55], v[20:35]
	ds_read_b64_tr_b16 v[52:53], v190 offset:56320
	ds_read_b64_tr_b16 v[54:55], v190 offset:56832
	s_waitcnt lgkmcnt(0)
	v_mfma_f32_32x32x16_bf16 v[36:51], v[124:127], v[52:55], v[36:51]
	s_branch .LBB0_345

.LBB0_500:
	s_lshl_b32 s3, s2, 2
	s_and_saveexec_b64 s[0:1], s[72:73]
	s_cbranch_execz .LBB0_254
	s_add_i32 s4, s3, 0
	s_add_i32 s4, s4, 0x21c10
	v_mov_b32_e32 v1, s4
	ds_write_b32 v1, v189
	s_branch .LBB0_254

; #define LAS __attribute__((address_space(3)))
; #define ATT_WAIT_BAR() asm volatile("s_waitcnt vmcnt(0) lgkmcnt(0)\n\ts_barrier" ::: "memory")
; __device__ __forceinline__ int next_unit(unsigned* ctr, LAS unsigned char* lds) {
;     ATT_WAIT_BAR();
;     if (threadIdx.x == 0) *(LAS unsigned*)(lds + A_UNIT) = __hip_atomic_fetch_add(ctr, 1u, __ATOMIC_RELAXED, __HIP_MEMORY_SCOPE_AGENT);
;     ATT_WAIT_BAR();
;     return (int)*(volatile LAS unsigned*)(lds + A_UNIT);
; }
.LBB0_915:
	s_or_b64 exec, exec, s[2:3]
	s_add_i32 s0, s0, 0
	s_add_i32 s0, s0, 0x21c10
	s_waitcnt vmcnt(0) lgkmcnt(0)
	s_barrier
	v_mov_b32_e32 v1, s0
	ds_read_b32 v1, v1
	s_movk_i32 s0, 0x1100
	s_xor_b32 s4, s4, 1
	s_waitcnt lgkmcnt(0)
	v_cmp_gt_i32_e32 vcc, s0, v1
	s_cbranch_vccz .LBB0_1163
.LBB0_916:
	v_mov_b32_e32 v187, v5
	s_and_saveexec_b64 s[2:3], s[76:77]
	s_cbranch_execz .LBB0_920
	s_mov_b64 s[8:9], exec
	v_mbcnt_lo_u32_b32 v2, s8, 0
	v_mbcnt_hi_u32_b32 v2, s9, v2
	v_cmp_eq_u32_e32 vcc, 0, v2
	s_and_saveexec_b64 s[6:7], vcc
	s_cbranch_execz .LBB0_919
	s_bcnt1_i32_b64 s0, s[8:9]
	v_mov_b32_e32 v3, s0
	v_readlane_b32 s0, v237, 11
	v_readlane_b32 s1, v237, 12
	s_nop 4
	global_atomic_add v3, v5, v3, s[0:1] sc0
.LBB0_919:
	s_or_b64 exec, exec, s[6:7]
	s_waitcnt vmcnt(0)
	v_readfirstlane_b32 s0, v3
	s_nop 1
	v_add_u32_e32 v187, s0, v2

; #define LAS __attribute__((address_space(3)))
; #define ATT_DMA(jt, slot) do { glds16(ksrc + (size_t)(jt) * 64 * D, (unsigned)__builtin_amdgcn_readfirstlane(lds0 + A_K + (slot) * 8192 + wid * 1024)); \
;                                glds16(vsrc + (size_t)(jt) * 64 * D, (unsigned)__builtin_amdgcn_readfirstlane(lds0 + A_V + (slot) * 8192 + wid * 1024)); } while (0)
; __device__ __forceinline__ void prompt_unit_sb(const Args& a, int l, int b, int h, int qb, LAS unsigned char* lds) {
;     int tid_ = threadIdx.x; asm volatile("" : "+v"(tid_));
;     const int tid = tid_, lane = tid & 63, r32 = lane & 31, hi = lane >> 5, wid = __builtin_amdgcn_readfirstlane(tid >> 6);
;     f16x8 T00, T01; make_tri(T00, T01, r32, hi);
;     const int q0 = qb * 256, jb = q0 / 64, jd = jb + (wid >> 1);
;     const int col = W + h * HD;
;     const size_t rowb = (size_t)b * T;
;     const bf16* Kh = (const bf16*)(a.ws + WS_K) + rowb * D + col; const bf16* Vh = (const bf16*)(a.ws + WS_V) + rowb * D + col;
;     const unsigned lds0 = (unsigned)(uintptr_t)lds;
;     const bf16* ksrc = Kh + (size_t)lane * D + wid * 8;
;     const bf16* vsrc = Vh + (size_t)(16 * (wid & 3) + (lane >> 2)) * D + (wid >> 2) * 32 + (lane & 3) * 8;
;     ...
;     ATT_DMA(jb + 3); ATT_DMA(jb + 2); ATT_DMA(jb + 1); ATT_DMA(jb);
;     if (jb >= 4) { ATT_DMA(jb - 1); ATT_DMA(jb - 2); ATT_DMA(jb - 3); }
;     bf16x8 qr[4];
;     { const bf16* Qw = (const bf16*)(a.ws + WS_Q) + (rowb + q0 + wid * 32 + r32) * D + col;
; #pragma unroll
;       for (int d0 = 0; d0 < 4; ++d0) qr[d0] = *(const bf16x8*)(Qw + d0 * 16 + hi * 8); }
;     const lds_cptr vp0 = (lds_cptr)lds + B_V + ((lane >> 4) & 1) * 32 + (lane & 3) * 8 + (4 * hi + ((lane & 15) >> 2)) * 64;
;     const int qlim = 32 * (wid & 1) + r32;
;     LAS float* wsf = (LAS float*)(lds + B_WSF) + wid * 64;
;     LAS unsigned* flags = (LAS unsigned*)(lds + B_FLAG);
;     FoxState st; st.m = 0.f; st.l = 0.f; st.mq = (bf16x8){}; st.o[0] = (f32x16){}; st.o[1] = (f32x16){};
;     float R = 0.f; bool done = false;
;     { ConvRegs cv; conv_load(cv, a, rowb + q0 + wid * 32, col, lane); conv_store<1>(cv, a, l, h, rowb + q0 + wid * 32, lane); }
.LBB0_928:
	v_lshrrev_b32_e32 v46, 5, v53
	v_and_b32_e32 v169, 31, v19
	v_lshlrev_b32_e32 v47, 2, v46
	v_cmp_lt_u32_e32 vcc, v47, v169
	v_or_b32_e32 v48, 16, v47
	v_or_b32_e32 v50, 1, v47
	v_cndmask_b32_e64 v3, v179, 0, vcc
	v_cmp_lt_u32_e32 vcc, v48, v169
	v_or_b32_e32 v49, 2, v47
	s_lshl_b32 s3, s7, 8
	v_cndmask_b32_e64 v24, v179, 0, vcc
	v_cmp_lt_u32_e32 vcc, v50, v169
	v_or_b32_e32 v52, 17, v47
	s_ashr_i32 s2, s8, 7
	v_cndmask_b32_e64 v14, v179, 0, vcc
	v_cmp_lt_u32_e32 vcc, v49, v169
	s_ashr_i32 s7, s3, 31
	v_or_b32_e32 v51, 18, v47
	v_cndmask_b32_e64 v15, v179, 0, vcc
	v_cmp_lt_u32_e32 vcc, v52, v169
	s_add_u32 s3, s3, s9
	v_or_b32_e32 v55, 3, v47
	v_cndmask_b32_e64 v25, v179, 0, vcc
	v_cmp_lt_u32_e32 vcc, v51, v169
	s_addc_u32 s7, s7, 0
	s_lshl_b32 s8, s84, 5
	v_cndmask_b32_e64 v26, v179, 0, vcc
	v_or_b32_e32 v54, 8, v47
	v_cmp_lt_u32_e32 vcc, v55, v169
	s_ashr_i32 s9, s8, 31
	v_or_b32_e32 v57, 19, v47
	v_cndmask_b32_e64 v16, v179, 0, vcc
	v_cmp_lt_u32_e32 vcc, v54, v169
	s_add_u32 s82, s3, s8
	v_or_b32_e32 v56, 24, v47
	v_cndmask_b32_e64 v17, v179, 0, vcc
	v_cmp_lt_u32_e32 vcc, v57, v169
	s_addc_u32 s83, s7, s9
	v_or_b32_e32 v58, 10, v47
	v_cndmask_b32_e64 v27, v179, 0, vcc
	v_cmp_lt_u32_e32 vcc, v56, v169
	v_or_b32_e32 v160, s82, v169
	v_mov_b32_e32 v161, s83
	v_readlane_b32 s10, v242, 28
	v_cndmask_b32_e64 v28, v179, 0, vcc
	v_or_b32_e32 v59, 9, v47
	v_cmp_lt_u32_e32 vcc, v58, v169
	v_lshlrev_b64 v[6:7], 11, v[160:161]
	v_readlane_b32 s11, v242, 29
	v_cndmask_b32_e64 v22, v179, 0, vcc
	v_cmp_lt_u32_e32 vcc, v59, v169
	v_or_b32_e32 v60, 26, v47
	v_lshl_add_u64 v[6:7], s[10:11], 0, v[6:7]
	s_lshl_b32 s78, s6, 1
	s_mov_b32 s79, s87
	v_lshrrev_b32_e32 v1, 3, v53
	v_cndmask_b32_e64 v23, v179, 0, vcc
	v_or_b32_e32 v61, 25, v47
	v_lshl_add_u64 v[6:7], v[6:7], 0, s[78:79]
	v_lshlrev_b32_e32 v4, 4, v46
	v_or_b32_e32 v160, s82, v1
	v_readlane_b32 s10, v242, 20
	v_cmp_lt_u32_e32 vcc, v60, v169
	v_lshl_add_u64 v[20:21], v[6:7], 0, v[4:5]
	v_lshlrev_b32_e32 v4, 3, v53
	v_lshlrev_b64 v[162:163], 11, v[160:161]
	v_readlane_b32 s11, v242, 21
	v_cndmask_b32_e64 v29, v179, 0, vcc
	v_cmp_lt_u32_e32 vcc, v61, v169
	v_or_b32_e32 v62, 11, v47
	v_readlane_b32 s12, v242, 22
	v_and_b32_e32 v168, 56, v4
	v_lshl_add_u64 v[6:7], s[10:11], 0, v[162:163]
	v_cndmask_b32_e64 v30, v179, 0, vcc
	v_readlane_b32 s13, v242, 23
	v_cmp_lt_u32_e32 vcc, v62, v169
	v_lshl_add_u64 v[6:7], v[6:7], 0, s[78:79]
	v_mov_b32_e32 v4, v168
	v_lshl_add_u64 v[10:11], s[12:13], 0, v[162:163]
	v_cndmask_b32_e64 v31, v179, 0, vcc
	v_lshl_add_u64 v[6:7], v[6:7], 0, v[4:5]
	v_lshl_add_u64 v[10:11], v[10:11], 0, s[78:79]
	v_pack_b32_f16 v118, v17, v23
	v_pack_b32_f16 v119, v22, v31
	v_or_b32_e32 v63, 27, v47
	v_or_b32_e32 v22, 0x4000, v162
	v_mov_b32_e32 v23, v163
	global_load_dwordx2 v[8:9], v[6:7], off offset:1088
	global_load_dwordx2 v[6:7], v[6:7], off offset:1024
	v_lshl_add_u64 v[10:11], v[10:11], 0, v[4:5]
	v_pack_b32_f16 v117, v15, v16
	v_pack_b32_f16 v116, v3, v14
	v_lshl_add_u64 v[14:15], s[10:11], 0, v[22:23]
	v_cmp_lt_u32_e32 vcc, v63, v169
	global_load_dwordx2 v[12:13], v[10:11], off offset:1088
	global_load_dwordx2 v[10:11], v[10:11], off offset:1024
	v_lshl_add_u64 v[14:15], v[14:15], 0, s[78:79]
	v_cndmask_b32_e64 v3, v179, 0, vcc
	v_lshl_add_u64 v[14:15], v[14:15], 0, v[4:5]
	v_pack_b32_f16 v123, v29, v3
	v_lshlrev_b32_e32 v3, 1, v19
	global_load_dwordx2 v[16:17], v[14:15], off offset:1088
	global_load_dwordx2 v[14:15], v[14:15], off offset:1024
	v_pack_b32_f16 v120, v24, v25
	v_and_b32_e32 v3, 32, v3
	s_add_i32 s3, 0, 0x10000
	v_lshlrev_b32_e32 v24, 4, v19
	global_load_dwordx4 v[124:127], v[20:21], off offset:1024
	global_load_dwordx4 v[128:131], v[20:21], off offset:1056
	global_load_dwordx4 v[132:135], v[20:21], off offset:1088
	global_load_dwordx4 v[136:139], v[20:21], off offset:1120
	v_lshl_add_u64 v[20:21], s[12:13], 0, v[22:23]
	v_add3_u32 v2, s3, v3, v2
	v_lshlrev_b32_e32 v3, 8, v46
	v_and_b32_e32 v24, 0xc0, v24
	v_lshl_add_u64 v[20:21], v[20:21], 0, s[78:79]
	v_add3_u32 v170, v2, v3, v24
	v_or_b32_e32 v2, 0x8000, v162
	v_mov_b32_e32 v3, v163
	v_lshl_add_u64 v[20:21], v[20:21], 0, v[4:5]
	v_lshl_add_u64 v[24:25], s[10:11], 0, v[2:3]
	global_load_dwordx2 v[22:23], v[20:21], off offset:1088
	global_load_dwordx2 v[20:21], v[20:21], off offset:1024
	v_lshl_add_u64 v[24:25], v[24:25], 0, s[78:79]
	v_lshl_add_u64 v[24:25], v[24:25], 0, v[4:5]
	v_lshl_add_u64 v[2:3], s[12:13], 0, v[2:3]
	v_pack_b32_f16 v121, v26, v27
	global_load_dwordx2 v[26:27], v[24:25], off offset:1088
	global_load_dwordx2 v[24:25], v[24:25], off offset:1024
	v_lshl_add_u64 v[2:3], v[2:3], 0, s[78:79]
	v_lshl_add_u64 v[2:3], v[2:3], 0, v[4:5]
	v_pack_b32_f16 v122, v28, v30
	global_load_dwordx2 v[30:31], v[2:3], off offset:1088
	global_load_dwordx2 v[28:29], v[2:3], off offset:1024
	v_or_b32_e32 v2, 0xc000, v162
	v_mov_b32_e32 v3, v163
	v_lshl_add_u64 v[32:33], s[10:11], 0, v[2:3]
	v_lshl_add_u64 v[32:33], v[32:33], 0, s[78:79]
	v_lshl_add_u64 v[2:3], s[12:13], 0, v[2:3]
	v_lshl_add_u64 v[32:33], v[32:33], 0, v[4:5]
	v_lshl_add_u64 v[2:3], v[2:3], 0, s[78:79]
	v_lshl_add_u64 v[2:3], v[2:3], 0, v[4:5]
	global_load_dwordx2 v[34:35], v[32:33], off offset:1088
	global_load_dwordx2 v[32:33], v[32:33], off offset:1024
	s_nop 0
	global_load_dwordx2 v[38:39], v[2:3], off offset:1088
	global_load_dwordx2 v[36:37], v[2:3], off offset:1024
	s_add_u32 s3, s82, 0x10000
	s_addc_u32 s7, s83, 0
	v_and_or_b32 v64, s8, 32, v169
	v_or_b32_e32 v2, s3, v1
	v_mov_b32_e32 v3, s7
	v_readlane_b32 s8, v242, 16
	v_lshlrev_b64 v[2:3], 11, v[2:3]
	v_readlane_b32 s9, v242, 17
	s_lshl_b32 s92, s6, 2
	v_readlane_b32 s6, v242, 24
	v_lshl_add_u64 v[40:41], s[8:9], 0, v[2:3]
	s_mov_b32 s93, s87
	v_readlane_b32 s7, v242, 25
	v_lshl_add_u64 v[40:41], v[40:41], 0, s[92:93]
	v_lshlrev_b32_e32 v4, 1, v168
	v_lshl_add_u64 v[2:3], s[6:7], 0, v[2:3]
	v_lshl_add_u64 v[44:45], v[40:41], 0, v[4:5]
	v_lshl_add_u64 v[2:3], v[2:3], 0, s[92:93]
	v_lshl_add_u64 v[2:3], v[2:3], 0, v[4:5]
	s_movk_i32 s3, 0x4000
	s_mov_b64 s[6:7], 0x4000
	v_lshlrev_b32_e32 v171, 10, v46
	v_cmp_lt_u32_e64 s[10:11], v50, v64
	v_cmp_lt_u32_e64 s[14:15], v49, v64
	v_cmp_lt_u32_e64 s[18:19], v55, v64
	v_cmp_lt_u32_e64 s[22:23], v54, v64
	v_cmp_lt_u32_e64 s[40:41], v48, v64
	v_cmp_lt_u32_e64 s[48:49], v51, v64
	v_or_b32_e32 v54, 58, v47
	v_or_b32_e32 v55, 59, v47
	v_mov_b32_e32 v4, v5
	s_mov_b32 s79, 0
	v_cmp_lt_u32_e64 s[26:27], v59, v64
	s_waitcnt vmcnt(0)
; #define LAS __attribute__((address_space(3)))
; __device__ __forceinline__ float bflo(unsigned w) { return __uint_as_float(w << 16); }
; __device__ __forceinline__ float bfhi(unsigned w) { return __uint_as_float(w & 0xffff0000u); }
; template <int TYPE>
; __device__ __forceinline__ void conv_store(const ConvRegs& c, const Args& a, int l, int h, size_t rowq, int lane) {
; #pragma unroll
;     for (int i = 0; i < 4; ++i) { const size_t grow = rowq + i * 8 + (lane >> 3);
;         float* ko = a.out + (TYPE == 0 ? O_FKP : O_SKP) + ((size_t)l * MP + grow) * W + h * HD + (lane & 7) * 8;
;         float* vo = a.out + (TYPE == 0 ? O_FVP : O_SVP) + ((size_t)l * MP + grow) * W + h * HD + (lane & 7) * 8;
;         const u32x4 kw = c.k[i], vw = c.v[i];
;         __builtin_nontemporal_store((f32x4){bflo(kw.x), bfhi(kw.x), bflo(kw.y), bfhi(kw.y)}, (f32x4*)ko); __builtin_nontemporal_store((f32x4){bflo(kw.z), bfhi(kw.z), bflo(kw.w), bfhi(kw.w)}, (f32x4*)(ko + 4));
;         __builtin_nontemporal_store((f32x4){bflo(vw.x), bfhi(vw.x), bflo(vw.y), bfhi(vw.y)}, (f32x4*)vo); __builtin_nontemporal_store((f32x4){bflo(vw.z), bfhi(vw.z), bflo(vw.w), bfhi(vw.w)}, (f32x4*)(vo + 4)); }
; }
; __device__ __forceinline__ void prompt_unit_sb(const Args& a, int l, int b, int h, int qb, LAS unsigned char* lds) {
;     ...
;     const lds_cptr vp0 = (lds_cptr)lds + B_V + ((lane >> 4) & 1) * 32 + (lane & 3) * 8 + (4 * hi + ((lane & 15) >> 2)) * 64;
;     const int qlim = 32 * (wid & 1) + r32;
;     LAS float* wsf = (LAS float*)(lds + B_WSF) + wid * 64;
;     LAS unsigned* flags = (LAS unsigned*)(lds + B_FLAG);
;     FoxState st; st.m = 0.f; st.l = 0.f; st.mq = (bf16x8){}; st.o[0] = (f32x16){}; st.o[1] = (f32x16){};
;     float R = 0.f; bool done = false;
;     { ConvRegs cv; conv_load(cv, a, rowb + q0 + wid * 32, col, lane); conv_store<1>(cv, a, l, h, rowb + q0 + wid * 32, lane); }
;     for (int it = 0; ; ++it) {
	v_lshlrev_b32_e32 v40, 16, v6
	v_and_b32_e32 v41, 0xffff0000, v6
	v_lshlrev_b32_e32 v42, 16, v7
	v_and_b32_e32 v43, 0xffff0000, v7
	v_lshlrev_b32_e32 v6, 16, v8
	v_and_b32_e32 v7, 0xffff0000, v8
	v_lshlrev_b32_e32 v8, 16, v9
	v_and_b32_e32 v9, 0xffff0000, v9
	global_store_dwordx4 v[44:45], v[6:9], off offset:128
	global_store_dwordx4 v[44:45], v[40:43], off
	v_cmp_lt_u32_e64 s[30:31], v58, v64
	v_lshlrev_b32_e32 v6, 16, v10
	v_and_b32_e32 v7, 0xffff0000, v10
	v_lshlrev_b32_e32 v8, 16, v11
	v_and_b32_e32 v9, 0xffff0000, v11
	global_store_dwordx4 v[2:3], v[6:9], off
	v_lshl_add_u64 v[10:11], v[44:45], 0, s[6:7]
	v_cmp_lt_u32_e64 s[36:37], v62, v64
	v_lshlrev_b32_e32 v6, 16, v12
	v_and_b32_e32 v7, 0xffff0000, v12
	v_lshlrev_b32_e32 v8, 16, v13
	v_and_b32_e32 v9, 0xffff0000, v13
	global_store_dwordx4 v[2:3], v[6:9], off offset:128
	v_lshl_add_u64 v[12:13], v[2:3], 0, s[6:7]
	s_mov_b64 s[6:7], 0x8000
	v_lshlrev_b32_e32 v6, 16, v14
	v_and_b32_e32 v7, 0xffff0000, v14
	v_add_co_u32_e32 v14, vcc, s3, v44
	v_lshlrev_b32_e32 v8, 16, v15
	v_and_b32_e32 v9, 0xffff0000, v15
	v_addc_co_u32_e32 v15, vcc, 0, v45, vcc
	global_store_dwordx4 v[14:15], v[6:9], off
	v_cmp_lt_u32_e64 s[44:45], v52, v64
	v_cmp_lt_u32_e64 s[52:53], v57, v64
	v_lshlrev_b32_e32 v6, 16, v16
	v_and_b32_e32 v7, 0xffff0000, v16
	v_lshlrev_b32_e32 v8, 16, v17
	v_and_b32_e32 v9, 0xffff0000, v17
	global_store_dwordx4 v[10:11], v[6:9], off offset:128
	v_add_co_u32_e32 v10, vcc, s3, v2
	s_nop 0
	v_lshlrev_b32_e32 v6, 16, v20
	v_and_b32_e32 v7, 0xffff0000, v20
	v_lshlrev_b32_e32 v8, 16, v21
	v_and_b32_e32 v9, 0xffff0000, v21
	v_addc_co_u32_e32 v11, vcc, 0, v3, vcc
	s_mov_b32 s3, 0x8000
	global_store_dwordx4 v[10:11], v[6:9], off
	v_add_co_u32_e32 v14, vcc, s3, v44
	s_nop 0
	v_lshlrev_b32_e32 v6, 16, v22
	v_and_b32_e32 v7, 0xffff0000, v22
	v_lshlrev_b32_e32 v8, 16, v23
	v_and_b32_e32 v9, 0xffff0000, v23
	global_store_dwordx4 v[12:13], v[6:9], off offset:128
	v_addc_co_u32_e32 v15, vcc, 0, v45, vcc
	s_nop 0
	v_lshlrev_b32_e32 v6, 16, v24
	v_and_b32_e32 v7, 0xffff0000, v24
	v_lshlrev_b32_e32 v8, 16, v25
	v_and_b32_e32 v9, 0xffff0000, v25
	v_lshl_add_u64 v[10:11], v[44:45], 0, s[6:7]
	global_store_dwordx4 v[14:15], v[6:9], off
	v_lshl_add_u64 v[12:13], v[2:3], 0, s[6:7]
	s_mov_b64 s[6:7], 0xc000
	v_lshlrev_b32_e32 v6, 16, v26
	v_and_b32_e32 v7, 0xffff0000, v26
	v_lshlrev_b32_e32 v8, 16, v27
	v_and_b32_e32 v9, 0xffff0000, v27
	global_store_dwordx4 v[10:11], v[6:9], off offset:128
	v_add_co_u32_e32 v10, vcc, s3, v2
	s_nop 0
	v_lshlrev_b32_e32 v6, 16, v28
	v_and_b32_e32 v7, 0xffff0000, v28
	v_lshlrev_b32_e32 v8, 16, v29
	v_and_b32_e32 v9, 0xffff0000, v29
	v_addc_co_u32_e32 v11, vcc, 0, v3, vcc
	s_mov_b32 s3, 0xc000
	global_store_dwordx4 v[10:11], v[6:9], off
	v_add_co_u32_e32 v14, vcc, s3, v44
	s_nop 0
	v_lshlrev_b32_e32 v6, 16, v30
	v_and_b32_e32 v7, 0xffff0000, v30
	v_lshlrev_b32_e32 v8, 16, v31
	v_and_b32_e32 v9, 0xffff0000, v31
	global_store_dwordx4 v[12:13], v[6:9], off offset:128
	v_addc_co_u32_e32 v15, vcc, 0, v45, vcc
	s_nop 0
	v_lshlrev_b32_e32 v6, 16, v32
	v_and_b32_e32 v7, 0xffff0000, v32
	v_lshlrev_b32_e32 v8, 16, v33
	v_and_b32_e32 v9, 0xffff0000, v33
	v_lshl_add_u64 v[10:11], v[44:45], 0, s[6:7]
	v_lshl_add_u64 v[12:13], v[2:3], 0, s[6:7]
	global_store_dwordx4 v[14:15], v[6:9], off
	v_add_co_u32_e32 v2, vcc, s3, v2
	s_nop 0
	v_lshlrev_b32_e32 v6, 16, v34
	v_and_b32_e32 v7, 0xffff0000, v34
	v_lshlrev_b32_e32 v8, 16, v35
	v_and_b32_e32 v9, 0xffff0000, v35
	global_store_dwordx4 v[10:11], v[6:9], off offset:128
	v_addc_co_u32_e32 v3, vcc, 0, v3, vcc
	s_nop 0
	v_lshlrev_b32_e32 v6, 16, v36
	v_and_b32_e32 v7, 0xffff0000, v36
	v_lshlrev_b32_e32 v8, 16, v37
	v_and_b32_e32 v9, 0xffff0000, v37
	global_store_dwordx4 v[2:3], v[6:9], off
	v_lshlrev_b32_e32 v2, 4, v169
	v_add3_u32 v172, 0, v171, v2
	v_or_b32_e32 v2, 32, v47
	v_cmp_lt_u32_e64 s[8:9], v2, v64
	v_or_b32_e32 v2, 33, v47
	v_cmp_lt_u32_e64 s[12:13], v2, v64
	v_or_b32_e32 v2, 34, v47
	v_cmp_lt_u32_e64 s[16:17], v2, v64
	v_or_b32_e32 v2, 35, v47
	v_cmp_lt_u32_e64 s[20:21], v2, v64
	v_or_b32_e32 v2, 40, v47
	v_cmp_lt_u32_e64 s[24:25], v2, v64
	v_or_b32_e32 v2, 41, v47
	v_cmp_lt_u32_e64 s[28:29], v2, v64
	v_or_b32_e32 v2, 42, v47
	v_cmp_lt_u32_e64 s[34:35], v2, v64
	v_or_b32_e32 v2, 43, v47
	v_cmp_lt_u32_e64 s[38:39], v2, v64
	v_or_b32_e32 v2, 48, v47
	v_cmp_lt_u32_e64 s[42:43], v2, v64
	v_or_b32_e32 v2, 49, v47
	v_cmp_lt_u32_e64 s[46:47], v2, v64
	v_or_b32_e32 v2, 50, v47
	v_cmp_lt_u32_e64 s[50:51], v2, v64
	v_or_b32_e32 v2, 51, v47
	v_cmp_lt_u32_e64 s[54:55], v2, v64
	v_or_b32_e32 v2, 56, v47
	v_lshlrev_b32_e32 v6, 16, v38
	v_and_b32_e32 v7, 0xffff0000, v38
	v_lshlrev_b32_e32 v8, 16, v39
	v_and_b32_e32 v9, 0xffff0000, v39
	s_lshl_b32 s3, s84, 2
	v_cmp_lt_u32_e64 s[58:59], v2, v64
	v_or_b32_e32 v2, 57, v47
	v_mov_b32_e32 v16, v5
	v_mov_b32_e32 v17, v5
	v_and_or_b32 v20, v181, 64, v169
	global_store_dwordx4 v[12:13], v[6:9], off offset:128
	s_add_i32 s93, s3, 0
	v_cmp_lt_u32_e64 s[6:7], v47, v64
	v_cmp_lt_u32_e64 s[62:63], v2, v64
	s_lshl_b32 s3, s1, 15
	s_lshl_b32 s1, s1, 2
	v_mov_b32_e32 v2, v5
	v_mov_b32_e32 v3, v5
	v_mov_b32_e32 v6, v5
	v_mov_b32_e32 v7, v5
	v_mov_b32_e32 v8, v5
	v_mov_b32_e32 v9, v5
	v_mov_b32_e32 v10, v5
	v_mov_b32_e32 v11, v5
	v_mov_b32_e32 v12, v5
	v_mov_b32_e32 v13, v5
	v_mov_b32_e32 v14, v5
	v_mov_b32_e32 v15, v5
	v_lshlrev_b32_e32 v173, 2, v20
	v_mov_b64_e32 v[34:35], v[16:17]
	v_mov_b64_e32 v[50:51], v[16:17]
	s_add_i32 s93, s93, 0x20c00
	v_cmp_lt_u32_e64 s[56:57], v56, v64
	v_cmp_lt_u32_e64 s[60:61], v61, v64
	v_cmp_lt_u32_e64 s[64:65], v60, v64
	s_lshl_b32 s95, s2, 13
	s_sub_i32 s96, 0x30000, s3
	s_sub_i32 s97, s2, s1
	s_sub_i32 s1, 0, s1
	v_mov_b32_e32 v52, 0
	s_mov_b32 s33, 28
	v_mov_b64_e32 v[32:33], v[14:15]
	v_mov_b64_e32 v[30:31], v[12:13]
	v_mov_b64_e32 v[28:29], v[10:11]
	v_mov_b64_e32 v[26:27], v[8:9]
	v_mov_b64_e32 v[24:25], v[6:7]
	v_mov_b64_e32 v[22:23], v[4:5]
	v_mov_b64_e32 v[20:21], v[2:3]
	v_mov_b64_e32 v[48:49], v[14:15]
	v_mov_b64_e32 v[46:47], v[12:13]
	v_mov_b64_e32 v[44:45], v[10:11]
	v_mov_b64_e32 v[42:43], v[8:9]
	v_mov_b64_e32 v[40:41], v[6:7]
	v_mov_b64_e32 v[38:39], v[4:5]
	v_mov_b64_e32 v[36:37], v[2:3]
	v_cmp_lt_u32_e64 s[66:67], v54, v64
	v_cmp_lt_u32_e64 s[68:69], v63, v64
	v_cmp_lt_u32_e64 s[70:71], v55, v64
	v_cmp_eq_u32_e64 s[72:73], 0, v53
	s_mov_b64 s[74:75], 0
	s_branch .LBB0_931

; #define ATT_WAIT_BAR() asm volatile("s_waitcnt vmcnt(0) lgkmcnt(0)\n\ts_barrier" ::: "memory")
; __device__ __forceinline__ void prompt_unit_fox(const Args& a, int l, int b, int h, int qb, LAS unsigned char* lds) {
;     ...
;         ATT_WAIT_BAR();
;         if (jp >= 1) ATT_DMA2(jp - 1, slot == 2 ? 0 : slot + 1);
.LBB0_964:
	s_waitcnt vmcnt(0) lgkmcnt(0)
	s_barrier
	s_cmp_lg_u32 s78, 0
	s_cbranch_scc0 .LBB0_995
	s_add_i32 s80, s78, -1
	s_mov_b32 s81, s87
	s_lshl_b32 s33, s93, 14
	s_lshl_b64 s[80:81], s[80:81], 18
	s_add_i32 s76, s33, 0x4000
	s_cmp_lg_u32 s93, 2
	s_cselect_b32 s76, s76, 0
	v_lshl_add_u64 v[20:21], v[170:171], 0, s[80:81]
	s_add_i32 s77, s96, s76
	s_mov_b32 s82, m0
	s_mov_b32 m0, s77
	s_nop 0
	global_load_lds_dwordx4 v[20:21], off
	s_mov_b32 m0, s82
	s_mov_b64 vcc, 0x20000
	v_lshl_add_u64 v[20:21], v[20:21], 0, vcc
	s_add_i32 s77, s97, s76
	s_mov_b32 s82, m0
	s_mov_b32 m0, s77
	s_nop 0
	global_load_lds_dwordx4 v[20:21], off
	s_mov_b32 m0, s82
	v_lshl_add_u64 v[20:21], v[172:173], 0, s[80:81]
	s_add_i32 s77, s84, s76
	s_mov_b32 s80, m0
	s_mov_b32 m0, s77
	s_nop 0
	global_load_lds_dwordx4 v[20:21], off
	s_mov_b32 m0, s80
	v_lshl_add_u64 v[20:21], v[20:21], 0, vcc
	s_add_i32 s76, s85, s76
	s_mov_b32 s77, m0
	s_mov_b32 m0, s76
	s_nop 0
	global_load_lds_dwordx4 v[20:21], off
	s_mov_b32 m0, s77
	s_cbranch_execnz .LBB0_967

; __device__ __forceinline__ void vfrags(VFrags& v, lds_cptr vp) {
; #pragma unroll
;     ...
; }
; __device__ __forceinline__ void pv(f32x16 (&o)[2], const VFrags& v, const u32x4& pw0, const u32x4& pw1, const u32x4& pw2, const u32x4& pw3) {
;     ...
;     o[0] = __builtin_amdgcn_mfma_f32_32x32x16_bf16(__builtin_bit_cast(bf16x8, pw0), ATT_VF(0), o[0], 0, 0, 0);
;     o[1] = __builtin_amdgcn_mfma_f32_32x32x16_bf16(__builtin_bit_cast(bf16x8, pw0), ATT_VF(4), o[1], 0, 0, 0);
;     o[0] = __builtin_amdgcn_mfma_f32_32x32x16_bf16(__builtin_bit_cast(bf16x8, pw1), ATT_VF(1), o[0], 0, 0, 0);
;     o[1] = __builtin_amdgcn_mfma_f32_32x32x16_bf16(__builtin_bit_cast(bf16x8, pw1), ATT_VF(5), o[1], 0, 0, 0);
;     o[0] = __builtin_amdgcn_mfma_f32_32x32x16_bf16(__builtin_bit_cast(bf16x8, pw2), ATT_VF(2), o[0], 0, 0, 0);
;     o[1] = __builtin_amdgcn_mfma_f32_32x32x16_bf16(__builtin_bit_cast(bf16x8, pw2), ATT_VF(6), o[1], 0, 0, 0);
;     o[0] = __builtin_amdgcn_mfma_f32_32x32x16_bf16(__builtin_bit_cast(bf16x8, pw3), ATT_VF(3), o[0], 0, 0, 0);
;     o[1] = __builtin_amdgcn_mfma_f32_32x32x16_bf16(__builtin_bit_cast(bf16x8, pw3), ATT_VF(7), o[1], 0, 0, 0);
;     ...
; }
; __device__ __forceinline__ void fox_pair_pv(FoxState& st, const PairP& pp, lds_cptr vpB) {
;     { VFrags vf; vfrags(vf, vpB + 8192); pv(st.o, vf, pp.w[0], pp.w[1], pp.w[2], pp.w[3]); }
;     { VFrags vf; vfrags(vf, vpB); pv(st.o, vf, pp.w[4], pp.w[5], pp.w[6], pp.w[7]); }
; }
.LBB0_967:
	s_andn2_b64 vcc, exec, s[2:3]
	s_cbranch_vccnz .LBB0_969
	v_lshl_add_u32 v3, s75, 14, v175
	ds_read_b64_tr_b16 v[20:21], v3 offset:57344
	ds_read_b64_tr_b16 v[22:23], v3 offset:57856
	ds_read_b64_tr_b16 v[24:25], v3 offset:58368
	ds_read_b64_tr_b16 v[26:27], v3 offset:58880
	s_waitcnt lgkmcnt(2)
	v_mfma_f32_32x32x16_bf16 v[68:83], v[152:155], v[20:23], v[68:83]
	ds_read_b64_tr_b16 v[20:21], v3 offset:61440
	ds_read_b64_tr_b16 v[22:23], v3 offset:61952
	ds_read_b64_tr_b16 v[28:29], v3 offset:62464
	ds_read_b64_tr_b16 v[30:31], v3 offset:62976
	s_waitcnt lgkmcnt(2)
	v_mfma_f32_32x32x16_bf16 v[52:67], v[152:155], v[20:23], v[52:67]
	v_mfma_f32_32x32x16_bf16 v[68:83], v[148:151], v[24:27], v[68:83]
	ds_read_b64_tr_b16 v[20:21], v3 offset:59392
	ds_read_b64_tr_b16 v[22:23], v3 offset:59904
	ds_read_b64_tr_b16 v[24:25], v3 offset:60416
	ds_read_b64_tr_b16 v[26:27], v3 offset:60928
	s_waitcnt lgkmcnt(4)
	v_mfma_f32_32x32x16_bf16 v[52:67], v[148:151], v[28:31], v[52:67]
	s_waitcnt lgkmcnt(2)
	v_mfma_f32_32x32x16_bf16 v[68:83], v[144:147], v[20:23], v[68:83]
	ds_read_b64_tr_b16 v[20:21], v3 offset:63488
	ds_read_b64_tr_b16 v[22:23], v3 offset:64000
	ds_read_b64_tr_b16 v[28:29], v3 offset:64512
	ds_read_b64_tr_b16 v[30:31], v3 offset:65024
	s_waitcnt lgkmcnt(2)
	v_mfma_f32_32x32x16_bf16 v[52:67], v[144:147], v[20:23], v[52:67]
	v_mfma_f32_32x32x16_bf16 v[68:83], v[140:143], v[24:27], v[68:83]
	ds_read_b64_tr_b16 v[20:21], v3 offset:49152
	ds_read_b64_tr_b16 v[22:23], v3 offset:49664
	ds_read_b64_tr_b16 v[24:25], v3 offset:50176
	ds_read_b64_tr_b16 v[26:27], v3 offset:50688
	s_waitcnt lgkmcnt(4)
	v_mfma_f32_32x32x16_bf16 v[52:67], v[140:143], v[28:31], v[52:67]
	s_waitcnt lgkmcnt(2)
	v_mfma_f32_32x32x16_bf16 v[68:83], v[136:139], v[20:23], v[68:83]
	ds_read_b64_tr_b16 v[20:21], v3 offset:53248
	ds_read_b64_tr_b16 v[22:23], v3 offset:53760
	ds_read_b64_tr_b16 v[28:29], v3 offset:54272
	ds_read_b64_tr_b16 v[30:31], v3 offset:54784
	s_waitcnt lgkmcnt(2)
	v_mfma_f32_32x32x16_bf16 v[52:67], v[136:139], v[20:23], v[52:67]
	v_mfma_f32_32x32x16_bf16 v[68:83], v[132:135], v[24:27], v[68:83]
	ds_read_b64_tr_b16 v[20:21], v3 offset:51200
	ds_read_b64_tr_b16 v[22:23], v3 offset:51712
	ds_read_b64_tr_b16 v[24:25], v3 offset:52224
	ds_read_b64_tr_b16 v[26:27], v3 offset:52736
	s_waitcnt lgkmcnt(4)
	v_mfma_f32_32x32x16_bf16 v[52:67], v[132:135], v[28:31], v[52:67]
	s_waitcnt lgkmcnt(2)
	v_mfma_f32_32x32x16_bf16 v[68:83], v[128:131], v[20:23], v[68:83]
	ds_read_b64_tr_b16 v[20:21], v3 offset:55296
	ds_read_b64_tr_b16 v[22:23], v3 offset:55808
	ds_read_b64_tr_b16 v[36:37], v3 offset:56320
	ds_read_b64_tr_b16 v[38:39], v3 offset:56832
	s_waitcnt lgkmcnt(2)
	v_mfma_f32_32x32x16_bf16 v[52:67], v[128:131], v[20:23], v[52:67]
	v_mfma_f32_32x32x16_bf16 v[68:83], v[124:127], v[24:27], v[68:83]
	s_waitcnt lgkmcnt(0)
	v_mfma_f32_32x32x16_bf16 v[52:67], v[124:127], v[36:39], v[52:67]

; #define LAS __attribute__((address_space(3)))
; __device__ __forceinline__ bool fox_pair_qs(FoxState& st, PairP& pp, lds_cptr kslotB, const bf16x8 (&qr)[4], const LAS u32x2* augB  , bool careful, int r32, int hi, LAS float* wsf) {
;     bf16x8 kfA[8], kfB[8]; kfrags(kfA, kslotB + 8192, r32, hi); kfrags(kfB, kslotB, r32, hi);
;     const u32x2 t0 = augB[64], t1 = augB[96], t2 = augB[0], t3 = augB[32];
;     const f32x16 zz = {};
;     f32x16 a0, a1, b0, b1;
;     a0 = __builtin_amdgcn_mfma_f32_32x32x16_bf16(__builtin_bit_cast(bf16x8, (u32x4){t0.x, t0.y, 0xBF80BF80u, 0u}), st.mq, zz, 0, 0, 0);
;     a1 = __builtin_amdgcn_mfma_f32_32x32x16_bf16(__builtin_bit_cast(bf16x8, (u32x4){t1.x, t1.y, 0xBF80BF80u, 0u}), st.mq, zz, 0, 0, 0);
;     b0 = __builtin_amdgcn_mfma_f32_32x32x16_bf16(__builtin_bit_cast(bf16x8, (u32x4){t2.x, t2.y, 0xBF80BF80u, 0u}), st.mq, zz, 0, 0, 0);
;     b1 = __builtin_amdgcn_mfma_f32_32x32x16_bf16(__builtin_bit_cast(bf16x8, (u32x4){t3.x, t3.y, 0xBF80BF80u, 0u}), st.mq, zz, 0, 0, 0);
; #pragma unroll
;     for (int d0 = 0; d0 < 4; ++d0) {
;         a0 = __builtin_amdgcn_mfma_f32_32x32x16_bf16(kfA[2 * d0], qr[d0], a0, 0, 0, 0); a1 = __builtin_amdgcn_mfma_f32_32x32x16_bf16(kfA[2 * d0 + 1], qr[d0], a1, 0, 0, 0);
;         b0 = __builtin_amdgcn_mfma_f32_32x32x16_bf16(kfB[2 * d0], qr[d0], b0, 0, 0, 0); b1 = __builtin_amdgcn_mfma_f32_32x32x16_bf16(kfB[2 * d0 + 1], qr[d0], b1, 0, 0, 0);
;     }
.LBB0_982:
	ds_read2_b64 v[52:55], v124 offset0:64 offset1:96
	v_mov_b64_e32 v[56:57], s[84:85]
	v_mov_b64_e32 v[58:59], s[86:87]
	ds_read_b128 v[126:129], v125 offset:8192
	ds_read2_b64 v[66:69], v124 offset1:32
	s_waitcnt lgkmcnt(2)
	v_mov_b32_e32 v56, v52
	v_mov_b32_e32 v57, v53
	v_mov_b64_e32 v[70:71], s[84:85]
	v_mov_b64_e32 v[72:73], s[86:87]
	s_waitcnt lgkmcnt(0)
	v_mov_b32_e32 v70, v68
	v_mfma_f32_32x32x16_bf16 v[84:99], v[56:59], v[160:163], 0
	v_mov_b64_e32 v[56:57], s[84:85]
	v_mov_b64_e32 v[58:59], s[86:87]
	v_mov_b32_e32 v56, v54
	v_mov_b32_e32 v57, v55
	v_mov_b64_e32 v[52:53], s[84:85]
	v_mov_b64_e32 v[54:55], s[86:87]
	v_mov_b32_e32 v52, v66
	v_mfma_f32_32x32x16_bf16 v[84:99], v[126:129], v[6:9], v[84:99]
	ds_read_b128 v[126:129], v125 offset:8704
	v_mov_b32_e32 v53, v67
	v_mov_b32_e32 v71, v69
	s_xor_b64 s[2:3], s[82:83], -1
	s_and_b64 vcc, exec, s[2:3]
	v_mfma_f32_32x32x16_bf16 v[100:115], v[56:59], v[160:163], 0
	s_waitcnt lgkmcnt(0)
	v_mfma_f32_32x32x16_bf16 v[100:115], v[126:129], v[6:9], v[100:115]
	ds_read_b128 v[126:129], v125
	v_mfma_f32_32x32x16_bf16 v[52:67], v[52:55], v[160:163], 0
	s_waitcnt lgkmcnt(0)
	v_mfma_f32_32x32x16_bf16 v[52:67], v[126:129], v[6:9], v[52:67]
	ds_read_b128 v[126:129], v125 offset:512
	v_mfma_f32_32x32x16_bf16 v[68:83], v[70:73], v[160:163], 0
	s_waitcnt lgkmcnt(0)
	v_mfma_f32_32x32x16_bf16 v[68:83], v[126:129], v[6:9], v[68:83]
	ds_read_b128 v[126:129], v125 offset:10240
	s_waitcnt lgkmcnt(0)
	v_mfma_f32_32x32x16_bf16 v[84:99], v[126:129], v[10:13], v[84:99]
	ds_read_b128 v[126:129], v125 offset:10752
	s_waitcnt lgkmcnt(0)
	v_mfma_f32_32x32x16_bf16 v[100:115], v[126:129], v[10:13], v[100:115]
	ds_read_b128 v[126:129], v125 offset:2048
	s_waitcnt lgkmcnt(0)
	v_mfma_f32_32x32x16_bf16 v[52:67], v[126:129], v[10:13], v[52:67]
	ds_read_b128 v[126:129], v125 offset:2560
	s_waitcnt lgkmcnt(0)
	v_mfma_f32_32x32x16_bf16 v[68:83], v[126:129], v[10:13], v[68:83]
	ds_read_b128 v[126:129], v125 offset:12288
	s_waitcnt lgkmcnt(0)
	v_mfma_f32_32x32x16_bf16 v[84:99], v[126:129], v[14:17], v[84:99]
	ds_read_b128 v[126:129], v125 offset:12800
	s_waitcnt lgkmcnt(0)
	v_mfma_f32_32x32x16_bf16 v[100:115], v[126:129], v[14:17], v[100:115]
	ds_read_b128 v[126:129], v125 offset:4096
	s_waitcnt lgkmcnt(0)
	v_mfma_f32_32x32x16_bf16 v[52:67], v[126:129], v[14:17], v[52:67]
	ds_read_b128 v[126:129], v125 offset:4608
	s_waitcnt lgkmcnt(0)
	v_mfma_f32_32x32x16_bf16 v[68:83], v[126:129], v[14:17], v[68:83]
	ds_read_b128 v[126:129], v125 offset:14336
	s_waitcnt lgkmcnt(0)
	v_mfma_f32_32x32x16_bf16 v[84:99], v[126:129], v[116:119], v[84:99]
	ds_read_b128 v[126:129], v125 offset:14848
	s_waitcnt lgkmcnt(0)
	v_mfma_f32_32x32x16_bf16 v[100:115], v[126:129], v[116:119], v[100:115]
	ds_read_b128 v[126:129], v125 offset:6144
	s_waitcnt lgkmcnt(0)
	v_mfma_f32_32x32x16_bf16 v[52:67], v[126:129], v[116:119], v[52:67]
	ds_read_b128 v[126:129], v125 offset:6656
	s_waitcnt lgkmcnt(0)
	v_mfma_f32_32x32x16_bf16 v[68:83], v[126:129], v[116:119], v[68:83]
	s_cbranch_vccnz .LBB0_986
; #define LAS __attribute__((address_space(3)))
; __device__ __forceinline__ float swap_max(float m) { auto rr = __builtin_amdgcn_permlane32_swap(__float_as_uint(m), __float_as_uint(m), false, false); return fmaxf(__uint_as_float(rr[0]), __uint_as_float(rr[1])); }
; __device__ __forceinline__ float max3f(float a, float b, float c) { return __builtin_fmaxf(__builtin_fmaxf(a, b), c); }
; #define ATT_LDS_WAIT() asm volatile("s_waitcnt lgkmcnt(0)" ::: "memory")
; __device__ __forceinline__ bool fox_pair_qs(FoxState& st, PairP& pp, lds_cptr kslotB, const bf16x8 (&qr)[4], const LAS u32x2* augB  , bool careful, int r32, int hi, LAS float* wsf) {
;     ...
;     if (careful) {
;         asm volatile("; careful pass: move the reference" ::: "memory");
;         float rm = max3f(a0[0], a1[0], b0[0]), rm2 = max3f(b1[0], a0[1], a1[1]);
;         rm = max3f(rm, b0[1], b1[1]);
; #pragma unroll
;         for (int r = 2; r < 16; ++r) { rm = max3f(rm, a0[r], a1[r]); rm2 = max3f(rm2, b0[r], b1[r]); }
;         rm = swap_max(max3f(rm, rm2, rm2));
;         const float dl = fmaxf(rm, 0.f);
;         st.m += dl; st.mq = make_mq(st.m, hi);
; #pragma unroll
;         for (int r = 0; r < 16; ++r) { a0[r] -= dl; a1[r] -= dl; b0[r] -= dl; b1[r] -= dl; }
;         const float f = __builtin_amdgcn_exp2f(-dl);
;         st.l *= f;
;         if (hi == 0) wsf[r32] = f;
;         ATT_LDS_WAIT();
; #pragma unroll
;         for (int g = 0; g < 4; ++g) { const f32x4 fv = *(const LAS f32x4*)(wsf + 8 * g + 4 * hi);
; #pragma unroll
;             for (int i = 0; i < 4; ++i) { st.o[0][4 * g + i] *= fv[i]; st.o[1][4 * g + i] *= fv[i]; } }
;     }
	s_nop 4
	v_max_f32_e32 v3, v100, v100
	v_max_f32_e32 v4, v84, v84
	v_max_f32_e32 v3, v4, v3
	s_nop 2
	v_max3_f32 v4, v68, v85, v101
	v_max3_f32 v3, v3, v52, v53
	v_max3_f32 v3, v3, v69, v86
	v_max3_f32 v4, v4, v54, v70
	v_max3_f32 v3, v3, v102, v87
	v_max3_f32 v4, v4, v55, v71
	v_max3_f32 v3, v3, v103, v88
	v_max3_f32 v4, v4, v56, v72
	v_max3_f32 v3, v3, v104, v89
	v_max3_f32 v4, v4, v57, v73
	v_max3_f32 v3, v3, v105, v90
	v_max3_f32 v4, v4, v58, v74
	v_max3_f32 v3, v3, v106, v91
	v_max3_f32 v4, v4, v59, v75
	v_max3_f32 v3, v3, v107, v92
	v_max3_f32 v4, v4, v60, v76
	v_max3_f32 v3, v3, v108, v93
	v_max3_f32 v4, v4, v61, v77
	v_max3_f32 v3, v3, v109, v94
	v_max3_f32 v4, v4, v62, v78
	v_max3_f32 v3, v3, v110, v95
	v_max3_f32 v4, v4, v63, v79
	v_max3_f32 v3, v3, v111, v96
	v_max3_f32 v4, v4, v64, v80
	v_max3_f32 v3, v3, v112, v97
	v_max3_f32 v4, v4, v65, v81
	v_max3_f32 v3, v3, v113, v98
	v_max3_f32 v4, v4, v66, v82
	v_max3_f32 v3, v3, v114, v99
	v_max3_f32 v4, v4, v67, v83
	v_max3_f32 v3, v3, v115, v4
	v_mov_b32_e32 v4, v3
	s_nop 1
	v_permlane32_swap_b32_e32 v3, v4
	v_max3_f32 v126, v3, v4, 0
	v_exp_f32_e64 v127, -v126
	s_and_saveexec_b64 vcc, s[6:7]
	ds_write_b32 v184, v127
	s_or_b64 exec, exec, vcc
	v_add_f32_e32 v191, v191, v126
	v_cvt_pk_bf16_f32 v3, v191, 0
	v_lshlrev_b32_e32 v3, 16, v3
	v_sub_f32_e32 v4, v191, v3
	v_cvt_pk_bf16_f32 v128, v4, 0
	v_lshlrev_b32_e32 v128, 16, v128
	v_sub_f32_e32 v4, v4, v128
	s_waitcnt lgkmcnt(0)
	v_add_u32_e32 v138, s89, v174
	v_cvt_pk_bf16_f32 v4, v128, v4
	v_sub_f32_e32 v99, v99, v126
	v_sub_f32_e32 v98, v98, v126
	v_sub_f32_e32 v97, v97, v126
	v_sub_f32_e32 v96, v96, v126
	v_sub_f32_e32 v95, v95, v126
	v_sub_f32_e32 v94, v94, v126
	v_sub_f32_e32 v93, v93, v126
	v_sub_f32_e32 v92, v92, v126
	v_sub_f32_e32 v91, v91, v126
	v_sub_f32_e32 v90, v90, v126
	v_sub_f32_e32 v89, v89, v126
	v_sub_f32_e32 v88, v88, v126
	v_sub_f32_e32 v87, v87, v126
	v_sub_f32_e32 v86, v86, v126
	v_sub_f32_e32 v85, v85, v126
	v_sub_f32_e32 v84, v84, v126
	v_sub_f32_e32 v115, v115, v126
	v_sub_f32_e32 v114, v114, v126
	v_sub_f32_e32 v113, v113, v126
	v_sub_f32_e32 v112, v112, v126
	v_sub_f32_e32 v111, v111, v126
	v_sub_f32_e32 v110, v110, v126
	v_sub_f32_e32 v109, v109, v126
	v_sub_f32_e32 v108, v108, v126
	v_sub_f32_e32 v107, v107, v126
	v_sub_f32_e32 v106, v106, v126
	v_sub_f32_e32 v105, v105, v126
	v_sub_f32_e32 v104, v104, v126
	v_sub_f32_e32 v103, v103, v126
	v_sub_f32_e32 v102, v102, v126
	v_sub_f32_e32 v101, v101, v126
	v_sub_f32_e32 v100, v100, v126
	v_sub_f32_e32 v67, v67, v126
	v_sub_f32_e32 v66, v66, v126
	v_sub_f32_e32 v65, v65, v126
	v_sub_f32_e32 v64, v64, v126
	v_sub_f32_e32 v63, v63, v126
	v_sub_f32_e32 v62, v62, v126
	v_sub_f32_e32 v61, v61, v126
	v_sub_f32_e32 v60, v60, v126
	v_sub_f32_e32 v59, v59, v126
	v_sub_f32_e32 v58, v58, v126
	v_sub_f32_e32 v57, v57, v126
	v_sub_f32_e32 v56, v56, v126
	v_sub_f32_e32 v55, v55, v126
	v_sub_f32_e32 v54, v54, v126
	v_sub_f32_e32 v53, v53, v126
	v_sub_f32_e32 v52, v52, v126
	v_sub_f32_e32 v83, v83, v126
	v_sub_f32_e32 v82, v82, v126
	v_sub_f32_e32 v81, v81, v126
	v_sub_f32_e32 v80, v80, v126
	v_sub_f32_e32 v79, v79, v126
	v_sub_f32_e32 v78, v78, v126
	v_sub_f32_e32 v77, v77, v126
	v_sub_f32_e32 v76, v76, v126
	v_sub_f32_e32 v75, v75, v126
	v_sub_f32_e32 v74, v74, v126
	v_sub_f32_e32 v73, v73, v126
	v_sub_f32_e32 v72, v72, v126
	v_sub_f32_e32 v71, v71, v126
	v_sub_f32_e32 v70, v70, v126
	v_sub_f32_e32 v69, v69, v126
	v_sub_f32_e32 v68, v68, v126
	v_mul_f32_e32 v194, v194, v127
	ds_read_b128 v[126:129], v138
	ds_read_b128 v[130:133], v138 offset:32
	ds_read_b128 v[134:137], v138 offset:64
	ds_read_b128 v[138:141], v138 offset:96
	v_cvt_pk_bf16_f32 v3, 1.0, v3
	v_cndmask_b32_e64 v4, 0, v4, s[6:7]
	v_cndmask_b32_e64 v3, 0, v3, s[6:7]
	v_mov_b64_e32 v[162:163], v[4:5]
	s_waitcnt lgkmcnt(0)
	v_pk_mul_f32 v[32:33], v[32:33], v[138:139]
	v_pk_mul_f32 v[28:29], v[28:29], v[134:135]
	v_pk_mul_f32 v[24:25], v[24:25], v[130:131]
	v_pk_mul_f32 v[34:35], v[34:35], v[140:141]
	v_pk_mul_f32 v[30:31], v[30:31], v[136:137]
	v_pk_mul_f32 v[26:27], v[26:27], v[132:133]
	v_pk_mul_f32 v[22:23], v[22:23], v[128:129]
	v_pk_mul_f32 v[20:21], v[20:21], v[126:127]
	v_pk_mul_f32 v[48:49], v[48:49], v[138:139]
	v_pk_mul_f32 v[44:45], v[44:45], v[134:135]
	v_pk_mul_f32 v[40:41], v[40:41], v[130:131]
	v_pk_mul_f32 v[50:51], v[50:51], v[140:141]
	v_pk_mul_f32 v[46:47], v[46:47], v[136:137]
	v_pk_mul_f32 v[42:43], v[42:43], v[132:133]
	v_pk_mul_f32 v[38:39], v[38:39], v[128:129]
	v_pk_mul_f32 v[36:37], v[36:37], v[126:127]
	v_mov_b64_e32 v[160:161], v[2:3]

; __device__ __forceinline__ unsigned cvtpk(float lo, float hi) { f32x2 v = {lo, hi}; bf16x2_t b = __builtin_convertvector(v, bf16x2_t); return __builtin_bit_cast(unsigned, b); }
; __device__ __forceinline__ float fadd_s(float a, float b) { float r = a + b; asm volatile("" : "+v"(r)); return r; }
; #define ATT_PACK4(P, B, F) (u32x4){F(P[B], P[B + 1]), F(P[B + 2], P[B + 3]), F(P[B + 4], P[B + 5]), F(P[B + 6], P[B + 7])}
; __device__ __forceinline__ bool fox_pair_qs(FoxState& st, PairP& pp, lds_cptr kslotB, const bf16x8 (&qr)[4], const LAS u32x2* augB  , bool careful, int r32, int hi, LAS float* wsf) {
;     ...
;     float sacc = 0.f, sacc2 = 0.f;
; #pragma unroll
;     for (int r = 0; r < 16; ++r) { a0[r] = __builtin_amdgcn_exp2f(a0[r]); a1[r] = __builtin_amdgcn_exp2f(a1[r]); sacc = fadd_s(sacc, a0[r]); sacc2 = fadd_s(sacc2, a1[r]); }
;     pp.w[0] = ATT_PACK4(a0, 0, cvtpk); pp.w[1] = ATT_PACK4(a0, 8, cvtpk); pp.w[2] = ATT_PACK4(a1, 0, cvtpk); pp.w[3] = ATT_PACK4(a1, 8, cvtpk);
; #pragma unroll
;     for (int r = 0; r < 16; ++r) { b0[r] = __builtin_amdgcn_exp2f(b0[r]); b1[r] = __builtin_amdgcn_exp2f(b1[r]); sacc = fadd_s(sacc, b0[r]); sacc2 = fadd_s(sacc2, b1[r]); }
;     pp.w[4] = ATT_PACK4(b0, 0, cvtpk); pp.w[5] = ATT_PACK4(b0, 8, cvtpk); pp.w[6] = ATT_PACK4(b1, 0, cvtpk); pp.w[7] = ATT_PACK4(b1, 8, cvtpk);
;     const float ts = fadd_s(sacc, sacc2);
;     if (!careful && __any(!(ts < FOX_BIG))) return false;
;     st.l = fadd_s(st.l, ts);
;     return true;
; }
; __device__ __forceinline__ void fox_pair_pv(FoxState& st, const PairP& pp, lds_cptr vpB) {
;     { VFrags vf; vfrags(vf, vpB + 8192); pv(st.o, vf, pp.w[0], pp.w[1], pp.w[2], pp.w[3]); }
;     { VFrags vf; vfrags(vf, vpB); pv(st.o, vf, pp.w[4], pp.w[5], pp.w[6], pp.w[7]); }
; }
.LBB0_993:
	v_cvt_pk_bf16_f32 v152, v84, v100
	v_cvt_pk_bf16_f32 v153, v101, v102
	v_cvt_pk_bf16_f32 v154, v103, v104
	v_cvt_pk_bf16_f32 v155, v105, v106
	v_cvt_pk_bf16_f32 v148, v107, v108
	v_cvt_pk_bf16_f32 v149, v109, v110
	v_cvt_pk_bf16_f32 v150, v111, v112
	v_cvt_pk_bf16_f32 v151, v113, v114
	v_cvt_pk_bf16_f32 v144, v3, v4
	v_cvt_pk_bf16_f32 v145, v85, v86
	v_cvt_pk_bf16_f32 v146, v87, v88
	v_cvt_pk_bf16_f32 v147, v89, v90
	v_cvt_pk_bf16_f32 v140, v91, v92
	v_cvt_pk_bf16_f32 v141, v93, v94
	v_cvt_pk_bf16_f32 v142, v95, v96
	v_cvt_pk_bf16_f32 v143, v97, v98
	v_cvt_pk_bf16_f32 v136, v99, v68
	v_cvt_pk_bf16_f32 v137, v69, v70
	v_cvt_pk_bf16_f32 v138, v71, v72
	v_cvt_pk_bf16_f32 v139, v73, v74
	v_cvt_pk_bf16_f32 v132, v75, v76
	v_cvt_pk_bf16_f32 v133, v77, v78
	v_cvt_pk_bf16_f32 v134, v79, v80
	v_cvt_pk_bf16_f32 v135, v81, v82
	v_cvt_pk_bf16_f32 v128, v52, v53
	v_cvt_pk_bf16_f32 v129, v54, v55
	v_cvt_pk_bf16_f32 v130, v56, v57
	v_cvt_pk_bf16_f32 v131, v58, v59
	v_cvt_pk_bf16_f32 v124, v60, v61
	v_cvt_pk_bf16_f32 v125, v62, v63
	v_cvt_pk_bf16_f32 v126, v64, v65
	v_cvt_pk_bf16_f32 v127, v66, v67
	s_andn2_b64 vcc, exec, s[90:91]
	s_mov_b64 s[2:3], -1
	s_cbranch_vccnz .LBB0_996
	ds_read_b64_tr_b16 v[52:53], v190 offset:57344
	ds_read_b64_tr_b16 v[54:55], v190 offset:57856
	s_mov_b64 s[2:3], 0
	s_waitcnt lgkmcnt(0)
	v_mfma_f32_32x32x16_bf16 v[20:35], v[152:155], v[52:55], v[20:35]
	ds_read_b64_tr_b16 v[52:53], v190 offset:61440
	ds_read_b64_tr_b16 v[54:55], v190 offset:61952
	s_waitcnt lgkmcnt(0)
	v_mfma_f32_32x32x16_bf16 v[36:51], v[152:155], v[52:55], v[36:51]
	ds_read_b64_tr_b16 v[52:53], v190 offset:58368
	ds_read_b64_tr_b16 v[54:55], v190 offset:58880
	s_waitcnt lgkmcnt(0)
	v_mfma_f32_32x32x16_bf16 v[20:35], v[148:151], v[52:55], v[20:35]
	ds_read_b64_tr_b16 v[52:53], v190 offset:62464
	ds_read_b64_tr_b16 v[54:55], v190 offset:62976
	s_waitcnt lgkmcnt(0)
	v_mfma_f32_32x32x16_bf16 v[36:51], v[148:151], v[52:55], v[36:51]
	ds_read_b64_tr_b16 v[52:53], v190 offset:59392
	ds_read_b64_tr_b16 v[54:55], v190 offset:59904
	s_waitcnt lgkmcnt(0)
	v_mfma_f32_32x32x16_bf16 v[20:35], v[144:147], v[52:55], v[20:35]
	ds_read_b64_tr_b16 v[52:53], v190 offset:63488
	ds_read_b64_tr_b16 v[54:55], v190 offset:64000
	s_waitcnt lgkmcnt(0)
	v_mfma_f32_32x32x16_bf16 v[36:51], v[144:147], v[52:55], v[36:51]
	ds_read_b64_tr_b16 v[52:53], v190 offset:60416
	ds_read_b64_tr_b16 v[54:55], v190 offset:60928
	s_waitcnt lgkmcnt(0)
	v_mfma_f32_32x32x16_bf16 v[20:35], v[140:143], v[52:55], v[20:35]
	ds_read_b64_tr_b16 v[52:53], v190 offset:64512
	ds_read_b64_tr_b16 v[54:55], v190 offset:65024
	s_waitcnt lgkmcnt(0)
	v_mfma_f32_32x32x16_bf16 v[36:51], v[140:143], v[52:55], v[36:51]
	ds_read_b64_tr_b16 v[52:53], v190 offset:49152
	ds_read_b64_tr_b16 v[54:55], v190 offset:49664
	s_waitcnt lgkmcnt(0)
	v_mfma_f32_32x32x16_bf16 v[20:35], v[136:139], v[52:55], v[20:35]
	ds_read_b64_tr_b16 v[52:53], v190 offset:53248
	ds_read_b64_tr_b16 v[54:55], v190 offset:53760
	s_waitcnt lgkmcnt(0)
	v_mfma_f32_32x32x16_bf16 v[36:51], v[136:139], v[52:55], v[36:51]
	ds_read_b64_tr_b16 v[52:53], v190 offset:50176
	ds_read_b64_tr_b16 v[54:55], v190 offset:50688
	s_waitcnt lgkmcnt(0)
	v_mfma_f32_32x32x16_bf16 v[20:35], v[132:135], v[52:55], v[20:35]
	ds_read_b64_tr_b16 v[52:53], v190 offset:54272
	ds_read_b64_tr_b16 v[54:55], v190 offset:54784
	s_waitcnt lgkmcnt(0)
	v_mfma_f32_32x32x16_bf16 v[36:51], v[132:135], v[52:55], v[36:51]
	ds_read_b64_tr_b16 v[52:53], v190 offset:51200
	ds_read_b64_tr_b16 v[54:55], v190 offset:51712
	s_waitcnt lgkmcnt(0)
	v_mfma_f32_32x32x16_bf16 v[20:35], v[128:131], v[52:55], v[20:35]
	ds_read_b64_tr_b16 v[52:53], v190 offset:55296
	ds_read_b64_tr_b16 v[54:55], v190 offset:55808
	s_waitcnt lgkmcnt(0)
	v_mfma_f32_32x32x16_bf16 v[36:51], v[128:131], v[52:55], v[36:51]
	ds_read_b64_tr_b16 v[52:53], v190 offset:52224
	ds_read_b64_tr_b16 v[54:55], v190 offset:52736
	s_waitcnt lgkmcnt(0)
	v_mfma_f32_32x32x16_bf16 v[20:35], v[124:127], v[52:55], v[20:35]
	ds_read_b64_tr_b16 v[52:53], v190 offset:56320
	ds_read_b64_tr_b16 v[54:55], v190 offset:56832
	s_waitcnt lgkmcnt(0)
	v_mfma_f32_32x32x16_bf16 v[36:51], v[124:127], v[52:55], v[36:51]
	s_branch .LBB0_997

.LBB0_1161:
	s_lshl_b32 s0, s4, 2
	s_and_saveexec_b64 s[2:3], s[76:77]
	s_cbranch_execz .LBB0_915
	s_add_i32 s1, s0, 0
	s_add_i32 s1, s1, 0x21c10
	v_mov_b32_e32 v1, s1
	ds_write_b32 v1, v187
	s_branch .LBB0_915

; #define LAS __attribute__((address_space(3)))
; __global__ void __launch_bounds__(NTHR, 2) fwd(Args a_in) {
;     extern __shared__ __attribute__((aligned(16))) unsigned char lds_raw[];
;     LAS unsigned char* lds = (LAS unsigned char*)lds_raw;
;     volatile LAS unsigned* MISC = (volatile LAS unsigned*)(lds + MISC_OFF);
;     if (threadIdx.x < 32) MISC[threadIdx.x] = 0u;
;     __syncthreads();
;     const KArgs kp0 = (KArgs)__builtin_amdgcn_kernarg_segment_ptr();
;     unsigned* ctl = (unsigned*)(a_in.ws + WS_CTL);
;     const bool multi = (a_in.ph_hi - a_in.ph_lo) > 1;
;     XcdBarrier bar; bar.bar = ctl + CW_BAR; bar.x = 0; bar.st = nullptr;
;     if (multi) bar = xcd_barrier_post(ctl + CW_BAR, MISC + 8);
;     const int lo = a_in.ph_lo, hi = a_in.ph_hi;
;     ...
;     run_layer<0>(kp0, lds, bar, lo, hi);
;     run_layer<1>(kp0, lds, bar, lo, hi);
;     if (IN(9)) { FRESH_IDS(); phase_final(a, gwave, nwaves, lane); if (PROBE_DOUBLE == 10) phase_final(a, gwave, nwaves, lane); }
;     ...
; }
	.amdhsa_kernel _Z3fwd4Args
		.amdhsa_group_segment_fixed_size 0
		.amdhsa_private_segment_fixed_size 0
		.amdhsa_kernarg_size 392
		.amdhsa_user_sgpr_count 2
		.amdhsa_user_sgpr_dispatch_ptr 0
		.amdhsa_user_sgpr_queue_ptr 0
		.amdhsa_user_sgpr_kernarg_segment_ptr 1
		.amdhsa_user_sgpr_dispatch_id 0
		.amdhsa_user_sgpr_kernarg_preload_length 0
		.amdhsa_user_sgpr_kernarg_preload_offset 0
		.amdhsa_user_sgpr_private_segment_size 0
		.amdhsa_uses_dynamic_stack 0
		.amdhsa_enable_private_segment 0
		.amdhsa_system_sgpr_workgroup_id_x 1
		.amdhsa_system_sgpr_workgroup_id_y 0
		.amdhsa_system_sgpr_workgroup_id_z 0
		.amdhsa_system_sgpr_workgroup_info 0
		.amdhsa_system_vgpr_workitem_id 0
		.amdhsa_next_free_vgpr 243
		.amdhsa_next_free_sgpr 98
		.amdhsa_accum_offset 244
		.amdhsa_reserve_vcc 1
		.amdhsa_float_round_mode_32 0
		.amdhsa_float_round_mode_16_64 0
		.amdhsa_float_denorm_mode_32 3
		.amdhsa_float_denorm_mode_16_64 3
		.amdhsa_dx10_clamp 1
		.amdhsa_ieee_mode 1
		.amdhsa_fp16_overflow 0
		.amdhsa_tg_split 0
		.amdhsa_exception_fp_ieee_invalid_op 0
		.amdhsa_exception_fp_denorm_src 0
		.amdhsa_exception_fp_ieee_div_zero 0
		.amdhsa_exception_fp_ieee_overflow 0
		.amdhsa_exception_fp_ieee_underflow 0
		.amdhsa_exception_fp_ieee_inexact 0
		.amdhsa_exception_int_div_zero 0
	.end_amdhsa_kernel

; #define LAS __attribute__((address_space(3)))
; __global__ void __launch_bounds__(NTHR, 2) fwd(Args a_in) {
;     extern __shared__ __attribute__((aligned(16))) unsigned char lds_raw[];
;     LAS unsigned char* lds = (LAS unsigned char*)lds_raw;
;     volatile LAS unsigned* MISC = (volatile LAS unsigned*)(lds + MISC_OFF);
;     if (threadIdx.x < 32) MISC[threadIdx.x] = 0u;
;     __syncthreads();
;     const KArgs kp0 = (KArgs)__builtin_amdgcn_kernarg_segment_ptr();
;     unsigned* ctl = (unsigned*)(a_in.ws + WS_CTL);
;     const bool multi = (a_in.ph_hi - a_in.ph_lo) > 1;
;     XcdBarrier bar; bar.bar = ctl + CW_BAR; bar.x = 0; bar.st = nullptr;
;     if (multi) bar = xcd_barrier_post(ctl + CW_BAR, MISC + 8);
;     const int lo = a_in.ph_lo, hi = a_in.ph_hi;
;     ...
;     run_layer<0>(kp0, lds, bar, lo, hi);
;     run_layer<1>(kp0, lds, bar, lo, hi);
;     if (IN(9)) { FRESH_IDS(); phase_final(a, gwave, nwaves, lane); if (PROBE_DOUBLE == 10) phase_final(a, gwave, nwaves, lane); }
;     ...
; }
amdhsa.kernels:
  - .agpr_count:     0
    .args:
      - .offset:         0
        .size:           136
        .value_kind:     by_value
      - .offset:         136
        .size:           4
        .value_kind:     hidden_block_count_x
      - .offset:         140
        .size:           4
        .value_kind:     hidden_block_count_y
      - .offset:         144
        .size:           4
        .value_kind:     hidden_block_count_z
      - .offset:         148
        .size:           2
        .value_kind:     hidden_group_size_x
      - .offset:         150
        .size:           2
        .value_kind:     hidden_group_size_y
      - .offset:         152
        .size:           2
        .value_kind:     hidden_group_size_z
      - .offset:         154
        .size:           2
        .value_kind:     hidden_remainder_x
      - .offset:         156
        .size:           2
        .value_kind:     hidden_remainder_y
      - .offset:         158
        .size:           2
        .value_kind:     hidden_remainder_z
      - .offset:         176
        .size:           8
        .value_kind:     hidden_global_offset_x
      - .offset:         184
        .size:           8
        .value_kind:     hidden_global_offset_y
      - .offset:         192
        .size:           8
        .value_kind:     hidden_global_offset_z
      - .offset:         200
        .size:           2
        .value_kind:     hidden_grid_dims
      - .offset:         256
        .size:           4
        .value_kind:     hidden_dynamic_lds_size
    .group_segment_fixed_size: 0
    .kernarg_segment_align: 8
    .kernarg_segment_size: 392
    .language:       OpenCL C
    .language_version:
      - 2
      - 0
    .max_flat_workgroup_size: 512
    .name:           _Z3fwd4Args
    .private_segment_fixed_size: 0
    .sgpr_count:     104
    .sgpr_spill_count: 137
    .symbol:         _Z3fwd4Args.kd
    .uniform_work_group_size: 1
    .uses_dynamic_stack: false
    .vgpr_count:     243
    .vgpr_spill_count: 0
    .wavefront_size: 64
